# LN3 row loop: rows prefetched a whole iteration ahead into registers, gain/bias/b_in hoisted so the loop body has no load waits (replaces the resident-wig finalize)
# speedup vs baseline: 1.0050x; 1.0050x over previous
; __device__ __forceinline__ void row_ln(f32x4 (&v)[4], const float* g, const float* b, int lane) {
;     ...
;     for (int j = 0; j < 4; ++j) { const f32x4 gg = *(const f32x4*)(g + RCOL(lane, j)), bb = *(const f32x4*)(b + RCOL(lane, j)); v[j] = v[j] * rstd * gg + bb; }
; __global__ void __launch_bounds__(NT, 2) fwd(const Args args) {
;     ...
;         if (IN(pb + 10)) { PHASE_BEGIN
;             const float* g = A.in[17] + ((size_t)L * 3 + 2) * D; const float* bb = A.in[18] + ((size_t)L * 3 + 2) * D; const bf16* X = WSP(bf16, WS_XB);
;             if (L + 1 < DEPTH) { stage_wig(A, F, L + 1); __syncthreads(); }
;             int m0, m1; row_range(F, m0, m1);
;             for (int m = m0; m < m1; m += 4) { u32x4 r[4][2];
; #pragma unroll
;                 for (int q = 0; q < 4; ++q) { const int mm = (m + q < m1) ? m + q : m1 - 1; row_raw(X + (size_t)mm * D, F.lane, r[q]); }
.LBB0_1693:
	v_mov_b32_e32 v1, s6
	v_lshl_add_u32 v1, s8, 3, v1
	v_readlane_b32 s12, v253, 53
	v_readlane_b32 s8, v253, 52
	s_nop 0
	v_min_i32_e32 v3, s12, v1
	v_mul_lo_u32 v4, s8, v1
	v_readfirstlane_b32 s11, v3
	v_readfirstlane_b32 s16, v4
	v_add_u32_e32 v3, v4, v3
	v_mov_b32_e32 v4, s8
	v_cmp_gt_i32_e32 vcc, s12, v1
	v_readfirstlane_b32 s6, v3
	s_nop 0
	v_addc_co_u32_e32 v1, vcc, v3, v4, vcc
	v_cmp_ge_i32_e32 vcc, v3, v1
	s_and_b64 s[12:13], vcc, exec
	v_readfirstlane_b32 s8, v1
	s_cbranch_scc1 .LBB0_1723
	s_mul_hi_i32 s12, s10, 0x3000
	s_mulk_i32 s10, 0x3000
	s_add_u32 s10, s10, 0x2000
	s_addc_u32 s12, s12, 0
	v_lshlrev_b32_e32 v4, 3, v0
	s_waitcnt lgkmcnt(0)
	s_add_u32 s14, s40, s10
	v_ashrrev_i32_e32 v5, 31, v4
	s_addc_u32 s15, s41, s12
	v_lshlrev_b64 v[6:7], 1, v[4:5]
	s_add_u32 s18, s42, s10
	v_lshl_add_u64 v[8:9], s[58:59], 0, v[6:7]
	s_mov_b64 s[26:27], 0xb880000
	s_addc_u32 s19, s43, s12
	v_lshl_add_u64 v[52:53], v[8:9], 0, s[26:27]
	v_lshlrev_b64 v[54:55], 2, v[4:5]
	s_mul_hi_i32 s13, s7, 0x6820
	s_mul_i32 s26, s7, 0x6820
	s_ashr_i32 s7, s6, 31
	s_add_i32 s12, s8, -1
	v_lshl_add_u64 v[56:57], s[14:15], 0, v[54:55]
	s_lshl_b64 s[14:15], s[6:7], 12
	s_add_u32 s14, s56, s14
	v_lshl_add_u64 v[58:59], s[18:19], 0, v[54:55]
	s_addc_u32 s15, s57, s15
	s_lshl_b64 s[18:19], s[6:7], 5
	v_ashrrev_i32_e32 v1, 31, v0
	s_add_u32 s18, s18, 0x1b000000
	s_addc_u32 s19, s19, 0
	v_lshlrev_b64 v[4:5], 2, v[0:1]
	v_lshl_add_u64 v[60:61], s[18:19], 0, v[4:5]
	s_lshl_b64 s[18:19], s[6:7], 11
	s_add_i32 s7, s11, s16
	s_add_i32 s10, s7, 3
	s_ashr_i32 s11, s10, 31
	s_lshl_b64 s[16:17], s[10:11], 5
	s_add_u32 s16, s16, 0x1b000000
	s_addc_u32 s17, s17, 0
	s_add_i32 s28, s7, 1
	v_lshl_add_u64 v[64:65], s[16:17], 0, v[4:5]
	s_lshl_b64 s[16:17], s[10:11], 11
	s_ashr_i32 s29, s28, 31
	v_lshl_add_u64 v[66:67], s[16:17], 0, v[6:7]
	s_lshl_b64 s[16:17], s[28:29], 12
	s_add_u32 s16, s56, s16
	s_addc_u32 s17, s57, s17
	s_lshl_b64 s[10:11], s[10:11], 12
	v_lshl_add_u64 v[62:63], s[18:19], 0, v[6:7]
	s_add_u32 s18, s56, s10
	s_addc_u32 s19, s57, s11
	s_add_i32 s10, s7, 2
	s_ashr_i32 s11, s10, 31
	s_lshl_b64 s[34:35], s[10:11], 5
	s_add_u32 s34, s34, 0x1b000000
	s_addc_u32 s35, s35, 0
	v_lshl_add_u64 v[68:69], s[34:35], 0, v[4:5]
	s_lshl_b64 s[34:35], s[10:11], 11
	v_lshl_add_u64 v[70:71], s[34:35], 0, v[6:7]
	s_lshl_b64 s[34:35], s[28:29], 11
	s_lshl_b64 s[10:11], s[10:11], 12
	v_lshl_add_u64 v[72:73], s[34:35], 0, v[6:7]
	s_add_u32 s34, s56, s10
	s_addc_u32 s35, s57, s11
	s_lshl_b64 s[10:11], s[28:29], 5
	s_add_u32 s10, s10, 0x1b000000
	s_addc_u32 s11, s11, 0
	v_lshlrev_b32_e32 v3, 5, v0
	v_cmp_gt_i32_e64 s[38:39], 8, v0
	v_cmp_eq_u32_e64 s[40:41], 1, v0
	v_cmp_eq_u32_e64 s[42:43], 2, v0
	v_cmp_eq_u32_e64 s[44:45], 3, v0
	v_cmp_eq_u32_e64 s[46:47], 4, v0
	v_cmp_eq_u32_e64 s[48:49], 5, v0
	v_cmp_eq_u32_e64 s[50:51], 6, v0
	v_cmp_eq_u32_e64 s[52:53], 7, v0
	v_lshl_add_u64 v[74:75], s[10:11], 0, v[4:5]
	global_load_dwordx4 v[104:107], v[56:57], off
	global_load_dwordx4 v[108:111], v[56:57], off offset:16
	global_load_dwordx4 v[112:115], v[56:57], off offset:2048
	global_load_dwordx4 v[116:119], v[56:57], off offset:2064
	global_load_dwordx4 v[120:123], v[58:59], off
	global_load_dwordx4 v[124:127], v[58:59], off offset:16
	global_load_dwordx4 v[128:131], v[58:59], off offset:2048
	global_load_dwordx4 v[132:135], v[58:59], off offset:2064
	s_and_b64 vcc, exec, s[4:5]
	s_cbranch_vccnz .Lpf3_nobin
	s_load_dwordx2 s[66:67], s[2:3], 0x50
	s_waitcnt lgkmcnt(0)
	s_add_u32 s66, s66, s26
	s_addc_u32 s67, s67, s13
	s_add_u32 s66, s66, 0x3000
	s_addc_u32 s67, s67, 0
	v_lshl_add_u64 v[170:171], v[0:1], 2, s[66:67]
	global_load_dword v168, v[170:171], off
.Lpf3_nobin:
	s_add_i32 s10, s6, 0
	s_min_i32 s10, s10, s12
	s_ashr_i32 s11, s10, 31
	s_lshl_b64 s[10:11], s[10:11], 11
	v_lshl_add_u64 v[170:171], v[52:53], 0, s[10:11]
	global_load_dwordx4 v[136:139], v[170:171], off
	global_load_dwordx4 v[140:143], v[170:171], off offset:1024
	s_add_i32 s10, s6, 1
	s_min_i32 s10, s10, s12
	s_ashr_i32 s11, s10, 31
	s_lshl_b64 s[10:11], s[10:11], 11
	v_lshl_add_u64 v[170:171], v[52:53], 0, s[10:11]
	global_load_dwordx4 v[144:147], v[170:171], off
	global_load_dwordx4 v[148:151], v[170:171], off offset:1024
	s_add_i32 s10, s6, 2
	s_min_i32 s10, s10, s12
	s_ashr_i32 s11, s10, 31
	s_lshl_b64 s[10:11], s[10:11], 11
	v_lshl_add_u64 v[170:171], v[52:53], 0, s[10:11]
	global_load_dwordx4 v[152:155], v[170:171], off
	global_load_dwordx4 v[156:159], v[170:171], off offset:1024
	s_add_i32 s10, s6, 3
	s_min_i32 s10, s10, s12
	s_ashr_i32 s11, s10, 31
	s_lshl_b64 s[10:11], s[10:11], 11
	v_lshl_add_u64 v[170:171], v[52:53], 0, s[10:11]
	global_load_dwordx4 v[160:163], v[170:171], off
	global_load_dwordx4 v[164:167], v[170:171], off offset:1024
	s_waitcnt vmcnt(0)
	s_branch .LBB0_1697

; __device__ __forceinline__ float wave_sum(float v) { return rdlane(dpp_sum63(v), 63); }
; __device__ __forceinline__ void row_ln(f32x4 (&v)[4], const float* g, const float* b, int lane) {
;     ...
;     for (int j = 0; j < 4; ++j) s += (v[j][0] + v[j][1]) + (v[j][2] + v[j][3]);
;     const float mean = wave_sum(s) * (1.f / D); float s2 = 0.f;
; __global__ void __launch_bounds__(NT, 2) fwd(const Args args) {
;     ...
;             for (int m = m0; m < m1; m += 4) { u32x4 r[4][2];
; #pragma unroll
;                 for (int q = 0; q < 4; ++q) { const int mm = (m + q < m1) ? m + q : m1 - 1; row_raw(X + (size_t)mm * D, F.lane, r[q]); }
; #pragma unroll
;                 for (int q = 0; q < 4; ++q) if (m + q < m1) { f32x4 v[4]; row_unpack(r[q], v); row_ln(v, g, bb, F.lane);
.LBB0_1697:
	s_add_i32 s28, s6, 1
	s_add_i32 s27, s6, 2
	s_add_i32 s7, s6, 3
	s_waitcnt vmcnt(12)
	v_mov_b64_e32 v[32:33], v[136:137]
	v_mov_b64_e32 v[34:35], v[138:139]
	v_mov_b64_e32 v[28:29], v[140:141]
	v_mov_b64_e32 v[30:31], v[142:143]
	v_mov_b64_e32 v[20:21], v[144:145]
	v_mov_b64_e32 v[22:23], v[146:147]
	v_mov_b64_e32 v[24:25], v[148:149]
	v_mov_b64_e32 v[26:27], v[150:151]
	v_mov_b64_e32 v[12:13], v[152:153]
	v_mov_b64_e32 v[14:15], v[154:155]
	v_mov_b64_e32 v[16:17], v[156:157]
	v_mov_b64_e32 v[18:19], v[158:159]
	v_mov_b64_e32 v[4:5], v[160:161]
	v_mov_b64_e32 v[6:7], v[162:163]
	v_mov_b64_e32 v[8:9], v[164:165]
	v_mov_b64_e32 v[10:11], v[166:167]
	s_add_i32 s10, s6, 4
	s_min_i32 s10, s10, s12
	s_ashr_i32 s11, s10, 31
	s_lshl_b64 s[10:11], s[10:11], 11
	v_lshl_add_u64 v[170:171], v[52:53], 0, s[10:11]
	global_load_dwordx4 v[136:139], v[170:171], off
	global_load_dwordx4 v[140:143], v[170:171], off offset:1024
	s_add_i32 s10, s6, 5
	s_min_i32 s10, s10, s12
	s_ashr_i32 s11, s10, 31
	s_lshl_b64 s[10:11], s[10:11], 11
	v_lshl_add_u64 v[170:171], v[52:53], 0, s[10:11]
	global_load_dwordx4 v[144:147], v[170:171], off
	global_load_dwordx4 v[148:151], v[170:171], off offset:1024
	s_add_i32 s10, s6, 6
	s_min_i32 s10, s10, s12
	s_ashr_i32 s11, s10, 31
	s_lshl_b64 s[10:11], s[10:11], 11
	v_lshl_add_u64 v[170:171], v[52:53], 0, s[10:11]
	global_load_dwordx4 v[152:155], v[170:171], off
	global_load_dwordx4 v[156:159], v[170:171], off offset:1024
	s_add_i32 s10, s6, 7
	s_min_i32 s10, s10, s12
	s_ashr_i32 s11, s10, 31
	s_lshl_b64 s[10:11], s[10:11], 11
	v_lshl_add_u64 v[170:171], v[52:53], 0, s[10:11]
	global_load_dwordx4 v[160:163], v[170:171], off
	global_load_dwordx4 v[164:167], v[170:171], off offset:1024
	s_nop 0
	v_lshlrev_b32_e32 v78, 16, v30
	v_and_b32_e32 v82, 0xffff0000, v30
	v_lshlrev_b32_e32 v76, 16, v31
	v_and_b32_e32 v80, 0xffff0000, v31
	s_nop 0
	v_lshlrev_b32_e32 v31, 16, v33
	v_lshlrev_b32_e32 v30, 16, v32
	v_and_b32_e32 v33, 0xffff0000, v33
	v_and_b32_e32 v32, 0xffff0000, v32
	v_lshlrev_b32_e32 v86, 16, v28
	v_and_b32_e32 v87, 0xffff0000, v28
	v_lshlrev_b32_e32 v84, 16, v29
	v_and_b32_e32 v85, 0xffff0000, v29
	v_pk_add_f32 v[28:29], v[30:31], v[32:33]
	v_and_b32_e32 v37, 0xffff0000, v35
	v_add_f32_e32 v28, v28, v29
	v_add_f32_e32 v81, 0, v28
	v_lshlrev_b32_e32 v29, 16, v35
	v_lshlrev_b32_e32 v28, 16, v34
	v_and_b32_e32 v36, 0xffff0000, v34
	v_pk_add_f32 v[34:35], v[28:29], v[36:37]
	v_add_f32_e32 v79, v86, v87
	v_pk_add_f32 v[34:35], v[34:35], v[34:35] op_sel_hi:[0,1]
	v_add_f32_e32 v83, v84, v85
	v_mov_b32_e32 v77, v35
	v_pk_add_f32 v[38:39], v[78:79], v[82:83]
	v_pk_add_f32 v[34:35], v[76:77], v[80:81]
	s_nop 0
	v_pk_add_f32 v[34:35], v[38:39], v[34:35]
	s_nop 0
	v_add_f32_e32 v34, v34, v35
	v_mov_b32_e32 v35, v2
	s_nop 0
	v_add_f32_dpp v34, v34, v34 quad_perm:[1,0,3,2] row_mask:0xf bank_mask:0xf bound_ctrl:1
	s_nop 1
	v_add_f32_dpp v34, v34, v34 quad_perm:[2,3,0,1] row_mask:0xf bank_mask:0xf bound_ctrl:1
	s_nop 1
	v_add_f32_dpp v34, v34, v34 row_half_mirror row_mask:0xf bank_mask:0xf bound_ctrl:1
	s_nop 1
	v_add_f32_dpp v34, v34, v34 row_mirror row_mask:0xf bank_mask:0xf bound_ctrl:1
	s_nop 1
	v_mov_b32_dpp v35, v34 row_bcast:15 row_mask:0xa bank_mask:0xf
	v_add_f32_e32 v34, v34, v35
	v_mov_b32_e32 v35, v2
	s_nop 1
	v_mov_b32_dpp v35, v34 row_bcast:31 row_mask:0xc bank_mask:0xf
	v_add_f32_e32 v34, v34, v35
	s_nop 0
	v_readlane_b32 s10, v34, 63
	s_nop 1
	v_fmac_f32_e32 v33, s10, v236
	v_fmac_f32_e32 v32, s10, v236
	v_fmac_f32_e32 v31, s10, v236
	v_fmac_f32_e32 v30, s10, v236
	v_mul_f32_e32 v34, v32, v32
	v_mul_f32_e32 v35, v33, v33
	v_fmac_f32_e32 v34, v30, v30
	v_fmac_f32_e32 v35, v31, v31
	v_fmac_f32_e32 v37, s10, v236
	v_fmac_f32_e32 v36, s10, v236
	v_add_f32_e32 v34, v34, v35
	v_fmac_f32_e32 v29, s10, v236
	v_fmac_f32_e32 v28, s10, v236
	v_mul_f32_e32 v35, v36, v36
	v_mul_f32_e32 v38, v37, v37
	v_fmac_f32_e32 v35, v28, v28
	v_fmac_f32_e32 v38, v29, v29
	v_add_f32_e32 v35, v35, v38
	v_fmac_f32_e32 v85, s10, v236
	v_fmac_f32_e32 v87, s10, v236
	v_add_f32_e32 v34, v34, v35
	v_fmac_f32_e32 v84, s10, v236
	v_fmac_f32_e32 v86, s10, v236
	v_mul_f32_e32 v35, v87, v87
	v_mul_f32_e32 v38, v85, v85
	v_fmac_f32_e32 v35, v86, v86
; __device__ __forceinline__ float wave_sum(float v) { return rdlane(dpp_sum63(v), 63); }
; __device__ __forceinline__ void row_ln(f32x4 (&v)[4], const float* g, const float* b, int lane) {
;     ...
;     for (int j = 0; j < 4; ++j) { v[j] = v[j] - mean; s2 += (v[j][0] * v[j][0] + v[j][1] * v[j][1]) + (v[j][2] * v[j][2] + v[j][3] * v[j][3]); }
;     const float rstd = 1.0f / sqrtf(wave_sum(s2) * (1.f / D) + LN_EPS);
; #pragma unroll
;     for (int j = 0; j < 4; ++j) { const f32x4 gg = *(const f32x4*)(g + RCOL(lane, j)), bb = *(const f32x4*)(b + RCOL(lane, j)); v[j] = v[j] * rstd * gg + bb; }
; __global__ void __launch_bounds__(NT, 2) fwd(const Args args) {
;     ...
;                 for (int q = 0; q < 4; ++q) if (m + q < m1) { f32x4 v[4]; row_unpack(r[q], v); row_ln(v, g, bb, F.lane);
;                     if (L + 1 < DEPTH) row_finalize(A, F, m + q, v, L + 1);
;                     else {
; #pragma unroll
;                         for (int j = 0; j < 4; ++j) *(f32x4*)(F.out + O_Y + (size_t)(m + q) * D + RCOL(F.lane, j)) = v[j]; } } }
	v_fmac_f32_e32 v38, v84, v84
	v_add_f32_e32 v35, v35, v38
	v_fmac_f32_e32 v80, s10, v236
	v_fmac_f32_e32 v82, s10, v236
	v_add_f32_e32 v34, v35, v34
	v_fmac_f32_e32 v76, s10, v236
	v_fmac_f32_e32 v78, s10, v236
	v_mul_f32_e32 v35, v82, v82
	v_mul_f32_e32 v38, v80, v80
	v_fmac_f32_e32 v35, v78, v78
	v_fmac_f32_e32 v38, v76, v76
	v_add_f32_e32 v35, v35, v38
	v_add_f32_e32 v34, v35, v34
	v_mov_b32_e32 v35, v2
	v_mov_b32_e32 v79, v82
	v_add_f32_dpp v34, v34, v34 quad_perm:[1,0,3,2] row_mask:0xf bank_mask:0xf bound_ctrl:1
	v_mov_b32_e32 v77, v80
	s_nop 0
	v_add_f32_dpp v34, v34, v34 quad_perm:[2,3,0,1] row_mask:0xf bank_mask:0xf bound_ctrl:1
	s_nop 1
	v_add_f32_dpp v34, v34, v34 row_half_mirror row_mask:0xf bank_mask:0xf bound_ctrl:1
	s_nop 1
	v_add_f32_dpp v34, v34, v34 row_mirror row_mask:0xf bank_mask:0xf bound_ctrl:1
	s_nop 1
	v_mov_b32_dpp v35, v34 row_bcast:15 row_mask:0xa bank_mask:0xf
	v_add_f32_e32 v34, v34, v35
	v_mov_b32_e32 v35, v2
	s_nop 1
	v_mov_b32_dpp v35, v34 row_bcast:31 row_mask:0xc bank_mask:0xf
	v_add_f32_e32 v34, v34, v35
	s_nop 0
	v_readlane_b32 s10, v34, 63
	s_nop 1
	v_fma_f32 v34, s10, v237, v252
	v_cmp_gt_f32_e32 vcc, s31, v34
	v_mul_f32_e32 v35, 0x4f800000, v34
	s_nop 0
	v_cndmask_b32_e32 v34, v34, v35, vcc
	v_sqrt_f32_e32 v35, v34
	s_nop 0
	v_add_u32_e32 v38, -1, v35
	v_fma_f32 v39, -v38, v35, v34
	v_cmp_ge_f32_e64 s[54:55], 0, v39
	v_add_u32_e32 v39, 1, v35
	s_nop 0
	v_cndmask_b32_e64 v38, v35, v38, s[54:55]
	v_fma_f32 v35, -v39, v35, v34
	v_cmp_lt_f32_e64 s[54:55], 0, v35
	s_nop 1
	v_cndmask_b32_e64 v35, v38, v39, s[54:55]
	v_mul_f32_e32 v38, 0x37800000, v35
	v_cndmask_b32_e32 v35, v35, v38, vcc
	v_cmp_class_f32_e32 vcc, v34, v234
	s_nop 1
	v_cndmask_b32_e32 v34, v35, v34, vcc
	v_div_scale_f32 v35, s[10:11], v34, v34, 1.0
	v_rcp_f32_e32 v38, v35
	s_mov_b64 s[10:11], -1
	v_fma_f32 v39, -v35, v38, 1.0
	v_fmac_f32_e32 v38, v39, v38
	v_div_scale_f32 v39, vcc, 1.0, v34, 1.0
	v_mul_f32_e32 v40, v39, v38
	v_fma_f32 v41, -v35, v40, v39
	v_fmac_f32_e32 v40, v41, v38
	v_fma_f32 v35, -v35, v40, v39
	v_div_fmas_f32 v35, v35, v38, v40
	v_mov_b64_e32 v[38:39], v[108:109]
	v_mov_b64_e32 v[40:41], v[110:111]
	v_mov_b64_e32 v[42:43], v[104:105]
	v_mov_b64_e32 v[44:45], v[106:107]
	v_mov_b64_e32 v[46:47], v[124:125]
	v_mov_b64_e32 v[48:49], v[126:127]
	v_mov_b64_e32 v[90:91], v[120:121]
	v_mov_b64_e32 v[92:93], v[122:123]
	v_div_fixup_f32 v88, v35, v34, 1.0
	v_mov_b32_e32 v35, v32
	v_mov_b32_e32 v32, v31
	v_mov_b32_e32 v34, v30
	v_pk_mul_f32 v[30:31], v[32:33], v[88:89] op_sel_hi:[1,0]
	v_pk_mul_f32 v[50:51], v[34:35], v[88:89] op_sel_hi:[1,0]
	v_pk_mul_f32 v[86:87], v[86:87], v[88:89] op_sel_hi:[1,0]
	v_pk_mul_f32 v[84:85], v[84:85], v[88:89] op_sel_hi:[1,0]
	s_andn2_b64 vcc, exec, s[4:5]
	s_nop 0
	v_pk_fma_f32 v[34:35], v[44:45], v[30:31], v[92:93]
	v_mov_b32_e32 v30, v28
	v_mov_b32_e32 v31, v36
	v_mov_b32_e32 v36, v29
	v_pk_fma_f32 v[32:33], v[42:43], v[50:51], v[90:91]
	v_pk_mul_f32 v[42:43], v[30:31], v[88:89] op_sel_hi:[1,0]
	v_pk_mul_f32 v[28:29], v[36:37], v[88:89] op_sel_hi:[1,0]
	s_nop 0
	v_pk_fma_f32 v[30:31], v[40:41], v[28:29], v[48:49]
	v_pk_fma_f32 v[28:29], v[38:39], v[42:43], v[46:47]
	v_mov_b64_e32 v[36:37], v[116:117]
	v_mov_b64_e32 v[38:39], v[118:119]
	v_mov_b64_e32 v[44:45], v[112:113]
	v_mov_b64_e32 v[46:47], v[114:115]
	v_mov_b64_e32 v[40:41], v[132:133]
	v_mov_b64_e32 v[42:43], v[134:135]
	v_mov_b64_e32 v[48:49], v[128:129]
	v_mov_b64_e32 v[50:51], v[130:131]
	s_nop 0
	v_pk_fma_f32 v[44:45], v[44:45], v[86:87], v[48:49]
	v_pk_mul_f32 v[48:49], v[78:79], v[88:89] op_sel_hi:[1,0]
	v_pk_fma_f32 v[46:47], v[46:47], v[84:85], v[50:51]
	v_pk_mul_f32 v[50:51], v[76:77], v[88:89] op_sel_hi:[1,0]
	v_pk_fma_f32 v[36:37], v[36:37], v[48:49], v[40:41]
	v_cndmask_b32_e64 v40, 0, 1, s[4:5]
	v_pk_fma_f32 v[38:39], v[38:39], v[50:51], v[42:43]
	v_cmp_ne_u32_e64 s[54:55], 1, v40
	s_cbranch_vccnz .LBB0_1700
	v_lshl_add_u64 v[40:41], s[14:15], 0, v[54:55]
	global_store_dwordx4 v[40:41], v[32:35], off
	global_store_dwordx4 v[40:41], v[28:31], off offset:16
	global_store_dwordx4 v[40:41], v[44:47], off offset:2048
	global_store_dwordx4 v[40:41], v[36:39], off offset:2064
	s_cbranch_execz .LBB0_1701

; #define LAS __attribute__((address_space(3)))
; __device__ __forceinline__ float wave_sum(float v) { return rdlane(dpp_sum63(v), 63); }
; __device__ __forceinline__ void row_finalize(CArgs& A, Frame& F, int m, const f32x4 (&v)[4], int Ln) {
;     row_store_bf(WSP(bf16, WS_X) + (size_t)m * D, F.lane, v);
;     const LAS float* wig = (const LAS float*)(F.lds + WIG_OFF); const float* b_in = A.in[10] + (size_t)Ln * DIN + 3072;
;     float r[8];
; #pragma unroll
;     for (int c = 0; c < 8; ++c) { float s = 0.f;
; #pragma unroll
;         for (int j = 0; j < 4; ++j) { const f32x4 w = *(const LAS f32x4*)(wig + c * 1024 + RCOL(F.lane, j)); s += (v[j][0] * w[0] + v[j][1] * w[1]) + (v[j][2] * w[2] + v[j][3] * w[3]); }
;         r[c] = wave_sum(s); if (c & 1) asm volatile("" ::: "memory"); }
.LBB0_1701:
	v_lshl_add_u64 v[48:49], s[58:59], 0, v[62:63]
	s_mov_b32 s10, 0x7680000
	v_add_co_u32_e32 v76, vcc, s10, v48
	v_add_u32_e32 v84, 0, v3
	v_cvt_pk_bf16_f32 v40, v32, v33
	v_cvt_pk_bf16_f32 v41, v34, v35
	v_cvt_pk_bf16_f32 v42, v28, v29
	v_cvt_pk_bf16_f32 v43, v30, v31
	s_nop 0
	v_addc_co_u32_e32 v77, vcc, 0, v49, vcc
	v_add_u32_e32 v78, 0x12000, v84
	global_store_dwordx4 v[76:77], v[40:43], off
	v_add_u32_e32 v80, 0x14000, v84
	s_nop 0
	v_cvt_pk_bf16_f32 v40, v44, v45
	v_cvt_pk_bf16_f32 v41, v46, v47
	v_cvt_pk_bf16_f32 v42, v36, v37
	v_cvt_pk_bf16_f32 v43, v38, v39
	ds_read_b128 v[48:51], v78
	global_store_dwordx4 v[76:77], v[40:43], off offset:1024
	ds_read_b128 v[40:43], v78 offset:16
	s_waitcnt lgkmcnt(1)
	v_mul_f32_e32 v49, v33, v49
	v_fmac_f32_e32 v49, v32, v48
	v_mul_f32_e32 v48, v35, v51
	s_waitcnt lgkmcnt(0)
	v_mul_f32_e32 v41, v29, v41
	v_fmac_f32_e32 v48, v34, v50
	v_fmac_f32_e32 v41, v28, v40
	v_mul_f32_e32 v40, v31, v43
	v_add_f32_e32 v48, v49, v48
	v_fmac_f32_e32 v40, v30, v42
	v_add_f32_e32 v76, 0, v48
	ds_read_b128 v[48:51], v78 offset:2048
	v_add_f32_e32 v40, v41, v40
	v_add_f32_e32 v76, v76, v40
	ds_read_b128 v[40:43], v78 offset:2064
	s_waitcnt lgkmcnt(1)
	v_mul_f32_e32 v49, v45, v49
	v_fmac_f32_e32 v49, v44, v48
	v_mul_f32_e32 v48, v47, v51
	s_waitcnt lgkmcnt(0)
	v_mul_f32_e32 v41, v37, v41
	v_fmac_f32_e32 v48, v46, v50
	v_fmac_f32_e32 v41, v36, v40
	v_mul_f32_e32 v40, v39, v43
	v_add_f32_e32 v48, v49, v48
	v_fmac_f32_e32 v40, v38, v42
	v_add_f32_e32 v48, v76, v48
	v_add_f32_e32 v40, v41, v40
	v_add_f32_e32 v40, v48, v40
	v_mov_b32_e32 v41, v2
	v_add_u32_e32 v76, 0x13000, v84
	v_add_f32_dpp v40, v40, v40 quad_perm:[1,0,3,2] row_mask:0xf bank_mask:0xf bound_ctrl:1
	v_mov_b32_e32 v49, v2
	s_nop 0
	v_add_f32_dpp v40, v40, v40 quad_perm:[2,3,0,1] row_mask:0xf bank_mask:0xf bound_ctrl:1
	s_nop 1
	v_add_f32_dpp v40, v40, v40 row_half_mirror row_mask:0xf bank_mask:0xf bound_ctrl:1
	s_nop 1
	v_add_f32_dpp v40, v40, v40 row_mirror row_mask:0xf bank_mask:0xf bound_ctrl:1
	s_nop 1
	v_mov_b32_dpp v41, v40 row_bcast:15 row_mask:0xa bank_mask:0xf
	v_add_f32_e32 v48, v40, v41
	ds_read_b128 v[40:43], v76
	s_nop 0
	v_mov_b32_dpp v49, v48 row_bcast:31 row_mask:0xc bank_mask:0xf
	v_add_f32_e32 v48, v48, v49
	s_nop 0
	v_readlane_b32 s29, v48, 63
	ds_read_b128 v[48:51], v76 offset:16
	s_waitcnt lgkmcnt(1)
	v_mul_f32_e32 v41, v33, v41
	v_fmac_f32_e32 v41, v32, v40
	v_mul_f32_e32 v40, v35, v43
	v_fmac_f32_e32 v40, v34, v42
	v_add_f32_e32 v40, v41, v40
	s_waitcnt lgkmcnt(0)
	v_mul_f32_e32 v49, v29, v49
	v_add_f32_e32 v77, 0, v40
	v_fmac_f32_e32 v49, v28, v48
	v_mul_f32_e32 v48, v31, v51
	ds_read_b128 v[40:43], v76 offset:2048
	v_fmac_f32_e32 v48, v30, v50
	v_add_f32_e32 v48, v49, v48
	v_add_f32_e32 v77, v77, v48
	ds_read_b128 v[48:51], v76 offset:2064
	s_waitcnt lgkmcnt(1)
	v_mul_f32_e32 v41, v45, v41
	v_fmac_f32_e32 v41, v44, v40
	v_mul_f32_e32 v40, v47, v43
	v_fmac_f32_e32 v40, v46, v42
	v_add_f32_e32 v40, v41, v40
	s_waitcnt lgkmcnt(0)
	v_mul_f32_e32 v41, v37, v49
	v_mul_f32_e32 v42, v39, v51
	v_fmac_f32_e32 v41, v36, v48
	v_fmac_f32_e32 v42, v38, v50
	v_add_f32_e32 v40, v77, v40
	v_add_f32_e32 v41, v41, v42
	v_add_f32_e32 v40, v40, v41
	v_mov_b32_e32 v41, v2
	s_nop 0
	v_add_f32_dpp v40, v40, v40 quad_perm:[1,0,3,2] row_mask:0xf bank_mask:0xf bound_ctrl:1
	s_nop 1
	v_add_f32_dpp v40, v40, v40 quad_perm:[2,3,0,1] row_mask:0xf bank_mask:0xf bound_ctrl:1
	s_nop 1
	v_add_f32_dpp v40, v40, v40 row_half_mirror row_mask:0xf bank_mask:0xf bound_ctrl:1
	s_nop 1
	v_add_f32_dpp v40, v40, v40 row_mirror row_mask:0xf bank_mask:0xf bound_ctrl:1
	s_nop 1
	v_mov_b32_dpp v41, v40 row_bcast:15 row_mask:0xa bank_mask:0xf
	v_add_f32_e32 v40, v40, v41
	v_mov_b32_e32 v41, v2
	s_nop 1
	v_mov_b32_dpp v41, v40 row_bcast:31 row_mask:0xc bank_mask:0xf
	v_add_f32_e32 v48, v40, v41
	ds_read_b128 v[40:43], v80
	v_readlane_b32 s36, v48, 63
	ds_read_b128 v[48:51], v80 offset:2064
	ds_read_b128 v[76:79], v80 offset:2048
	ds_read_b128 v[80:83], v80 offset:16
	s_waitcnt lgkmcnt(3)
	v_mul_f32_e32 v41, v33, v41
	v_fmac_f32_e32 v41, v32, v40
	v_mul_f32_e32 v40, v35, v43
	v_fmac_f32_e32 v40, v34, v42
	v_add_f32_e32 v40, v41, v40
	s_waitcnt lgkmcnt(0)
	v_mul_f32_e32 v41, v29, v81
	v_mul_f32_e32 v42, v31, v83
	v_fmac_f32_e32 v41, v28, v80
	v_fmac_f32_e32 v42, v30, v82
	v_add_f32_e32 v40, 0, v40
	v_add_f32_e32 v41, v41, v42
	v_add_f32_e32 v40, v41, v40
	v_mul_f32_e32 v41, v45, v77
	v_mul_f32_e32 v42, v47, v79
	v_fmac_f32_e32 v41, v44, v76
	v_fmac_f32_e32 v42, v46, v78
	v_add_f32_e32 v41, v41, v42
	v_add_f32_e32 v40, v41, v40
	v_mul_f32_e32 v41, v37, v49
	v_mul_f32_e32 v42, v39, v51
	v_fmac_f32_e32 v41, v36, v48
	v_fmac_f32_e32 v42, v38, v50
	v_add_f32_e32 v41, v41, v42
	v_add_f32_e32 v40, v41, v40
	v_mov_b32_e32 v41, v2
	v_add_u32_e32 v76, 0x15000, v84
	v_add_f32_dpp v40, v40, v40 quad_perm:[1,0,3,2] row_mask:0xf bank_mask:0xf bound_ctrl:1
	v_mov_b32_e32 v49, v2
	v_add_u32_e32 v80, 0x18000, v84
	v_add_f32_dpp v40, v40, v40 quad_perm:[2,3,0,1] row_mask:0xf bank_mask:0xf bound_ctrl:1
	s_nop 1
	v_add_f32_dpp v40, v40, v40 row_half_mirror row_mask:0xf bank_mask:0xf bound_ctrl:1
	s_nop 1
	v_add_f32_dpp v40, v40, v40 row_mirror row_mask:0xf bank_mask:0xf bound_ctrl:1
	s_nop 1
	v_mov_b32_dpp v41, v40 row_bcast:15 row_mask:0xa bank_mask:0xf
	v_add_f32_e32 v48, v40, v41
	ds_read_b128 v[40:43], v76
	s_nop 0
	v_mov_b32_dpp v49, v48 row_bcast:31 row_mask:0xc bank_mask:0xf
	v_add_f32_e32 v48, v48, v49
	s_nop 0
	v_readlane_b32 s37, v48, 63
	ds_read_b128 v[48:51], v76 offset:16
	s_waitcnt lgkmcnt(1)
; #define LAS __attribute__((address_space(3)))
; __device__ __forceinline__ float wave_sum(float v) { return rdlane(dpp_sum63(v), 63); }
; __device__ __forceinline__ void row_finalize(CArgs& A, Frame& F, int m, const f32x4 (&v)[4], int Ln) {
;     ...
;     for (int c = 0; c < 8; ++c) { float s = 0.f;
; #pragma unroll
;         for (int j = 0; j < 4; ++j) { const f32x4 w = *(const LAS f32x4*)(wig + c * 1024 + RCOL(F.lane, j)); s += (v[j][0] * w[0] + v[j][1] * w[1]) + (v[j][2] * w[2] + v[j][3] * w[3]); }
;         r[c] = wave_sum(s); if (c & 1) asm volatile("" ::: "memory"); }
	v_mul_f32_e32 v41, v33, v41
	v_fmac_f32_e32 v41, v32, v40
	v_mul_f32_e32 v40, v35, v43
	v_fmac_f32_e32 v40, v34, v42
	v_add_f32_e32 v40, v41, v40
	s_waitcnt lgkmcnt(0)
	v_mul_f32_e32 v49, v29, v49
	v_add_f32_e32 v77, 0, v40
	v_fmac_f32_e32 v49, v28, v48
	v_mul_f32_e32 v48, v31, v51
	ds_read_b128 v[40:43], v76 offset:2048
	v_fmac_f32_e32 v48, v30, v50
	v_add_f32_e32 v48, v49, v48
	v_add_f32_e32 v77, v77, v48
	ds_read_b128 v[48:51], v76 offset:2064
	s_waitcnt lgkmcnt(1)
	v_mul_f32_e32 v41, v45, v41
	v_fmac_f32_e32 v41, v44, v40
	v_mul_f32_e32 v40, v47, v43
	v_fmac_f32_e32 v40, v46, v42
	v_add_f32_e32 v40, v41, v40
	s_waitcnt lgkmcnt(0)
	v_mul_f32_e32 v41, v37, v49
	v_mul_f32_e32 v42, v39, v51
	v_fmac_f32_e32 v41, v36, v48
	v_fmac_f32_e32 v42, v38, v50
	v_add_f32_e32 v40, v77, v40
	v_add_f32_e32 v41, v41, v42
	v_add_f32_e32 v40, v40, v41
	v_mov_b32_e32 v41, v2
	v_add_u32_e32 v76, 0x16000, v84
	v_add_f32_dpp v40, v40, v40 quad_perm:[1,0,3,2] row_mask:0xf bank_mask:0xf bound_ctrl:1
	v_mov_b32_e32 v49, v2
	s_nop 0
	v_add_f32_dpp v40, v40, v40 quad_perm:[2,3,0,1] row_mask:0xf bank_mask:0xf bound_ctrl:1
	s_nop 1
	v_add_f32_dpp v40, v40, v40 row_half_mirror row_mask:0xf bank_mask:0xf bound_ctrl:1
	s_nop 1
	v_add_f32_dpp v40, v40, v40 row_mirror row_mask:0xf bank_mask:0xf bound_ctrl:1
	s_nop 1
	v_mov_b32_dpp v41, v40 row_bcast:15 row_mask:0xa bank_mask:0xf
	v_add_f32_e32 v48, v40, v41
	ds_read_b128 v[40:43], v76
	s_nop 0
	v_mov_b32_dpp v49, v48 row_bcast:31 row_mask:0xc bank_mask:0xf
	v_add_f32_e32 v48, v48, v49
	s_nop 0
	v_readlane_b32 s56, v48, 63
	ds_read_b128 v[48:51], v76 offset:16
	s_waitcnt lgkmcnt(1)
	v_mul_f32_e32 v41, v33, v41
	v_fmac_f32_e32 v41, v32, v40
	v_mul_f32_e32 v40, v35, v43
	v_fmac_f32_e32 v40, v34, v42
	v_add_f32_e32 v40, v41, v40
	s_waitcnt lgkmcnt(0)
	v_mul_f32_e32 v49, v29, v49
	v_add_f32_e32 v77, 0, v40
	v_fmac_f32_e32 v49, v28, v48
	v_mul_f32_e32 v48, v31, v51
	ds_read_b128 v[40:43], v76 offset:2048
	v_fmac_f32_e32 v48, v30, v50
	v_add_f32_e32 v48, v49, v48
	v_add_f32_e32 v77, v77, v48
	ds_read_b128 v[48:51], v76 offset:2064
	s_waitcnt lgkmcnt(1)
	v_mul_f32_e32 v41, v45, v41
	v_fmac_f32_e32 v41, v44, v40
	v_mul_f32_e32 v40, v47, v43
	v_fmac_f32_e32 v40, v46, v42
	v_add_f32_e32 v40, v41, v40
	s_waitcnt lgkmcnt(0)
	v_mul_f32_e32 v41, v37, v49
	v_mul_f32_e32 v42, v39, v51
	v_fmac_f32_e32 v41, v36, v48
	v_fmac_f32_e32 v42, v38, v50
	v_add_f32_e32 v40, v77, v40
	v_add_f32_e32 v41, v41, v42
	v_add_f32_e32 v40, v40, v41
	v_mov_b32_e32 v41, v2
	v_add_u32_e32 v76, 0x17000, v84
	v_add_f32_dpp v40, v40, v40 quad_perm:[1,0,3,2] row_mask:0xf bank_mask:0xf bound_ctrl:1
	v_mov_b32_e32 v49, v2
	s_nop 0
	v_add_f32_dpp v40, v40, v40 quad_perm:[2,3,0,1] row_mask:0xf bank_mask:0xf bound_ctrl:1
	s_nop 1
	v_add_f32_dpp v40, v40, v40 row_half_mirror row_mask:0xf bank_mask:0xf bound_ctrl:1
	s_nop 1
	v_add_f32_dpp v40, v40, v40 row_mirror row_mask:0xf bank_mask:0xf bound_ctrl:1
	s_nop 1
	v_mov_b32_dpp v41, v40 row_bcast:15 row_mask:0xa bank_mask:0xf
	v_add_f32_e32 v48, v40, v41
	ds_read_b128 v[40:43], v76
	s_nop 0
	v_mov_b32_dpp v49, v48 row_bcast:31 row_mask:0xc bank_mask:0xf
	v_add_f32_e32 v48, v48, v49
	s_nop 0
	v_readlane_b32 s57, v48, 63
	ds_read_b128 v[48:51], v76 offset:16
	s_waitcnt lgkmcnt(1)
	v_mul_f32_e32 v41, v33, v41
	v_fmac_f32_e32 v41, v32, v40
	v_mul_f32_e32 v40, v35, v43
	v_fmac_f32_e32 v40, v34, v42
	v_add_f32_e32 v40, v41, v40
	s_waitcnt lgkmcnt(0)
	v_mul_f32_e32 v49, v29, v49
	v_add_f32_e32 v77, 0, v40
	v_fmac_f32_e32 v49, v28, v48
	v_mul_f32_e32 v48, v31, v51
	ds_read_b128 v[40:43], v76 offset:2048
	v_fmac_f32_e32 v48, v30, v50
	v_add_f32_e32 v48, v49, v48
	v_add_f32_e32 v77, v77, v48
	ds_read_b128 v[48:51], v76 offset:2064
	s_waitcnt lgkmcnt(1)
	v_mul_f32_e32 v41, v45, v41
	v_fmac_f32_e32 v41, v44, v40
	v_mul_f32_e32 v40, v47, v43
	v_fmac_f32_e32 v40, v46, v42
	v_add_f32_e32 v40, v41, v40
	s_waitcnt lgkmcnt(0)
	v_mul_f32_e32 v41, v37, v49
	v_mul_f32_e32 v42, v39, v51
	v_fmac_f32_e32 v41, v36, v48
	v_fmac_f32_e32 v42, v38, v50
	v_add_f32_e32 v40, v77, v40
	v_add_f32_e32 v41, v41, v42
	v_add_f32_e32 v40, v40, v41
	v_mov_b32_e32 v41, v2
	s_nop 0
	v_add_f32_dpp v40, v40, v40 quad_perm:[1,0,3,2] row_mask:0xf bank_mask:0xf bound_ctrl:1
	s_nop 1
	v_add_f32_dpp v40, v40, v40 quad_perm:[2,3,0,1] row_mask:0xf bank_mask:0xf bound_ctrl:1
	s_nop 1
	v_add_f32_dpp v40, v40, v40 row_half_mirror row_mask:0xf bank_mask:0xf bound_ctrl:1
	s_nop 1
	v_add_f32_dpp v40, v40, v40 row_mirror row_mask:0xf bank_mask:0xf bound_ctrl:1
	s_nop 1
	v_mov_b32_dpp v41, v40 row_bcast:15 row_mask:0xa bank_mask:0xf
	v_add_f32_e32 v40, v40, v41
	v_mov_b32_e32 v41, v2
	s_nop 1
	v_mov_b32_dpp v41, v40 row_bcast:31 row_mask:0xc bank_mask:0xf
	v_add_f32_e32 v48, v40, v41
	ds_read_b128 v[40:43], v80
	v_readlane_b32 s60, v48, 63
	ds_read_b128 v[48:51], v80 offset:2064
	ds_read_b128 v[76:79], v80 offset:2048
	ds_read_b128 v[80:83], v80 offset:16
	s_waitcnt lgkmcnt(3)
; #define LAS __attribute__((address_space(3)))
; __device__ __forceinline__ float wave_sum(float v) { return rdlane(dpp_sum63(v), 63); }
; __device__ __forceinline__ void row_finalize(CArgs& A, Frame& F, int m, const f32x4 (&v)[4], int Ln) {
;     ...
;     for (int c = 0; c < 8; ++c) { float s = 0.f;
; #pragma unroll
;         for (int j = 0; j < 4; ++j) { const f32x4 w = *(const LAS f32x4*)(wig + c * 1024 + RCOL(F.lane, j)); s += (v[j][0] * w[0] + v[j][1] * w[1]) + (v[j][2] * w[2] + v[j][3] * w[3]); }
;         r[c] = wave_sum(s); if (c & 1) asm volatile("" ::: "memory"); }
;     if (F.lane < 8) { float x = r[0];
; #pragma unroll
;         for (int c = 1; c < 8; ++c) x = (F.lane == c) ? r[c] : x;
;         WSP(float, WS_IGFG)[(size_t)m * 8 + F.lane] = x + b_in[F.lane]; }
	v_mul_f32_e32 v41, v33, v41
	v_fmac_f32_e32 v41, v32, v40
	v_mul_f32_e32 v40, v35, v43
	v_fmac_f32_e32 v40, v34, v42
	v_add_f32_e32 v40, v41, v40
	s_waitcnt lgkmcnt(0)
	v_mul_f32_e32 v41, v29, v81
	v_mul_f32_e32 v42, v31, v83
	v_fmac_f32_e32 v41, v28, v80
	v_fmac_f32_e32 v42, v30, v82
	v_add_f32_e32 v40, 0, v40
	v_add_f32_e32 v41, v41, v42
	v_add_f32_e32 v40, v41, v40
	v_mul_f32_e32 v41, v45, v77
	v_mul_f32_e32 v42, v47, v79
	v_fmac_f32_e32 v41, v44, v76
	v_fmac_f32_e32 v42, v46, v78
	v_add_f32_e32 v41, v41, v42
	v_add_f32_e32 v40, v41, v40
	v_mul_f32_e32 v41, v37, v49
	v_mul_f32_e32 v42, v39, v51
	v_fmac_f32_e32 v41, v36, v48
	v_fmac_f32_e32 v42, v38, v50
	v_add_f32_e32 v41, v41, v42
	v_add_f32_e32 v40, v41, v40
	v_mov_b32_e32 v41, v2
	v_mov_b32_e32 v49, v2
	v_add_f32_dpp v40, v40, v40 quad_perm:[1,0,3,2] row_mask:0xf bank_mask:0xf bound_ctrl:1
	v_add_u32_e32 v76, 0x19000, v84
	s_nop 0
	v_add_f32_dpp v40, v40, v40 quad_perm:[2,3,0,1] row_mask:0xf bank_mask:0xf bound_ctrl:1
	s_nop 1
	v_add_f32_dpp v40, v40, v40 row_half_mirror row_mask:0xf bank_mask:0xf bound_ctrl:1
	s_nop 1
	v_add_f32_dpp v40, v40, v40 row_mirror row_mask:0xf bank_mask:0xf bound_ctrl:1
	s_nop 1
	v_mov_b32_dpp v41, v40 row_bcast:15 row_mask:0xa bank_mask:0xf
	v_add_f32_e32 v48, v40, v41
	ds_read_b128 v[40:43], v76
	s_nop 0
	v_mov_b32_dpp v49, v48 row_bcast:31 row_mask:0xc bank_mask:0xf
	v_add_f32_e32 v48, v48, v49
	s_nop 0
	v_readlane_b32 s61, v48, 63
	ds_read_b128 v[48:51], v76 offset:16
	s_waitcnt lgkmcnt(1)
	v_mul_f32_e32 v33, v33, v41
	v_fmac_f32_e32 v33, v32, v40
	v_mul_f32_e32 v32, v35, v43
	v_fmac_f32_e32 v32, v34, v42
	s_waitcnt lgkmcnt(0)
	v_mul_f32_e32 v29, v29, v49
	v_fmac_f32_e32 v29, v28, v48
	v_mul_f32_e32 v28, v31, v51
	v_add_f32_e32 v32, v33, v32
	v_fmac_f32_e32 v28, v30, v50
	v_add_f32_e32 v40, 0, v32
	ds_read_b128 v[32:35], v76 offset:2048
	v_add_f32_e32 v28, v29, v28
	v_add_f32_e32 v40, v40, v28
	ds_read_b128 v[28:31], v76 offset:2064
	s_waitcnt lgkmcnt(1)
	v_mul_f32_e32 v33, v45, v33
	v_fmac_f32_e32 v33, v44, v32
	v_mul_f32_e32 v32, v47, v35
	s_waitcnt lgkmcnt(0)
	v_mul_f32_e32 v29, v37, v29
	v_fmac_f32_e32 v32, v46, v34
	v_fmac_f32_e32 v29, v36, v28
	v_mul_f32_e32 v28, v39, v31
	v_add_f32_e32 v32, v33, v32
	v_fmac_f32_e32 v28, v38, v30
	v_add_f32_e32 v32, v40, v32
	v_add_f32_e32 v28, v29, v28
	v_add_f32_e32 v28, v32, v28
	v_mov_b32_e32 v29, v2
	s_nop 0
	v_add_f32_dpp v28, v28, v28 quad_perm:[1,0,3,2] row_mask:0xf bank_mask:0xf bound_ctrl:1
	s_nop 1
	v_add_f32_dpp v28, v28, v28 quad_perm:[2,3,0,1] row_mask:0xf bank_mask:0xf bound_ctrl:1
	s_nop 1
	v_add_f32_dpp v28, v28, v28 row_half_mirror row_mask:0xf bank_mask:0xf bound_ctrl:1
	s_nop 1
	v_add_f32_dpp v28, v28, v28 row_mirror row_mask:0xf bank_mask:0xf bound_ctrl:1
	s_nop 1
	v_mov_b32_dpp v29, v28 row_bcast:15 row_mask:0xa bank_mask:0xf
	v_add_f32_e32 v28, v28, v29
	v_mov_b32_e32 v29, v2
	s_nop 1
	v_mov_b32_dpp v29, v28 row_bcast:31 row_mask:0xc bank_mask:0xf
	v_add_f32_e32 v28, v28, v29
	s_nop 0
	v_readlane_b32 s64, v28, 63
	s_and_saveexec_b64 s[10:11], s[38:39]
	s_cbranch_execz .LBB0_1703
	s_load_dwordx2 s[66:67], s[2:3], 0x50
	v_mov_b32_e32 v28, s29
	v_mov_b32_e32 v29, s36
	v_cndmask_b32_e64 v28, v28, v29, s[40:41]
	v_mov_b32_e32 v29, s37
	v_cndmask_b32_e64 v28, v28, v29, s[42:43]
	v_mov_b32_e32 v29, s56
	v_cndmask_b32_e64 v28, v28, v29, s[44:45]
	v_mov_b32_e32 v29, s57
	v_cndmask_b32_e64 v28, v28, v29, s[46:47]
	v_mov_b32_e32 v29, s60
	s_waitcnt lgkmcnt(0)
	s_add_u32 s66, s66, s26
	v_cndmask_b32_e64 v28, v28, v29, s[48:49]
	v_mov_b32_e32 v29, s61
	s_addc_u32 s67, s67, s13
	v_cndmask_b32_e64 v28, v28, v29, s[50:51]
	v_mov_b32_e32 v29, s64
	v_cndmask_b32_e64 v30, v28, v29, s[52:53]
	v_lshl_add_u64 v[28:29], v[0:1], 2, s[66:67]
	v_add_co_u32_e32 v28, vcc, 0x3000, v28
	s_nop 1
	v_addc_co_u32_e32 v29, vcc, 0, v29, vcc
	v_mov_b32_e32 v28, v168
	s_nop 0
	v_add_f32_e32 v30, v30, v28
	v_lshl_add_u64 v[28:29], s[58:59], 0, v[60:61]
	global_store_dword v[28:29], v30, off

; __device__ __forceinline__ float bflo(unsigned w) { return __uint_as_float(w << 16); }
; __device__ __forceinline__ float bfhi(unsigned w) { return __uint_as_float(w & 0xffff0000u); }
; __device__ __forceinline__ float wave_sum(float v) { return rdlane(dpp_sum63(v), 63); }
; __device__ __forceinline__ void row_unpack(const u32x4 (&r)[2], f32x4 (&v)[4]) {
; #pragma unroll
;     for (int j = 0; j < 2; ++j) { v[2 * j] = (f32x4){bflo(r[j].x), bfhi(r[j].x), bflo(r[j].y), bfhi(r[j].y)}; v[2 * j + 1] = (f32x4){bflo(r[j].z), bfhi(r[j].z), bflo(r[j].w), bfhi(r[j].w)}; }
; }
; __device__ __forceinline__ void row_ln(f32x4 (&v)[4], const float* g, const float* b, int lane) {
;     float s = 0.f;
; #pragma unroll
;     for (int j = 0; j < 4; ++j) s += (v[j][0] + v[j][1]) + (v[j][2] + v[j][3]);
;     const float mean = wave_sum(s) * (1.f / D); float s2 = 0.f;
; #pragma unroll
;     for (int j = 0; j < 4; ++j) { v[j] = v[j] - mean; s2 += (v[j][0] * v[j][0] + v[j][1] * v[j][1]) + (v[j][2] * v[j][2] + v[j][3] * v[j][3]); }
;     const float rstd = 1.0f / sqrtf(wave_sum(s2) * (1.f / D) + LN_EPS);
; #pragma unroll
;     for (int j = 0; j < 4; ++j) { const f32x4 gg = *(const f32x4*)(g + RCOL(lane, j)), bb = *(const f32x4*)(b + RCOL(lane, j)); v[j] = v[j] * rstd * gg + bb; }
.LBB0_1704:
	v_lshlrev_b32_e32 v78, 16, v24
	v_and_b32_e32 v79, 0xffff0000, v24
	v_lshlrev_b32_e32 v76, 16, v25
	v_and_b32_e32 v77, 0xffff0000, v25
	v_lshlrev_b32_e32 v25, 16, v21
	v_lshlrev_b32_e32 v24, 16, v20
	v_and_b32_e32 v21, 0xffff0000, v21
	v_and_b32_e32 v20, 0xffff0000, v20
	v_lshlrev_b32_e32 v46, 16, v26
	v_and_b32_e32 v50, 0xffff0000, v26
	v_lshlrev_b32_e32 v44, 16, v27
	v_and_b32_e32 v48, 0xffff0000, v27
	v_pk_add_f32 v[26:27], v[24:25], v[20:21]
	v_lshlrev_b32_e32 v29, 16, v23
	v_add_f32_e32 v26, v26, v27
	v_lshlrev_b32_e32 v28, 16, v22
	v_and_b32_e32 v23, 0xffff0000, v23
	v_and_b32_e32 v22, 0xffff0000, v22
	v_add_f32_e32 v49, 0, v26
	v_pk_add_f32 v[26:27], v[28:29], v[22:23]
	v_add_f32_e32 v47, v78, v79
	v_pk_add_f32 v[26:27], v[26:27], v[26:27] op_sel_hi:[0,1]
	v_add_f32_e32 v51, v76, v77
	v_mov_b32_e32 v45, v27
	v_pk_add_f32 v[30:31], v[46:47], v[50:51]
	v_pk_add_f32 v[26:27], v[44:45], v[48:49]
	s_nop 0
	v_pk_add_f32 v[26:27], v[30:31], v[26:27]
	s_nop 0
	v_add_f32_e32 v26, v26, v27
	v_mov_b32_e32 v27, v2
	s_nop 0
	v_add_f32_dpp v26, v26, v26 quad_perm:[1,0,3,2] row_mask:0xf bank_mask:0xf bound_ctrl:1
	s_nop 1
	v_add_f32_dpp v26, v26, v26 quad_perm:[2,3,0,1] row_mask:0xf bank_mask:0xf bound_ctrl:1
	s_nop 1
	v_add_f32_dpp v26, v26, v26 row_half_mirror row_mask:0xf bank_mask:0xf bound_ctrl:1
	s_nop 1
	v_add_f32_dpp v26, v26, v26 row_mirror row_mask:0xf bank_mask:0xf bound_ctrl:1
	s_nop 1
	v_mov_b32_dpp v27, v26 row_bcast:15 row_mask:0xa bank_mask:0xf
	v_add_f32_e32 v26, v26, v27
	v_mov_b32_e32 v27, v2
	s_nop 1
	v_mov_b32_dpp v27, v26 row_bcast:31 row_mask:0xc bank_mask:0xf
	v_add_f32_e32 v26, v26, v27
	s_nop 0
	v_readlane_b32 s10, v26, 63
	s_nop 1
	v_fmac_f32_e32 v21, s10, v236
	v_fmac_f32_e32 v20, s10, v236
	v_fmac_f32_e32 v25, s10, v236
	v_fmac_f32_e32 v24, s10, v236
	v_mul_f32_e32 v26, v20, v20
	v_mul_f32_e32 v27, v21, v21
	v_fmac_f32_e32 v26, v24, v24
	v_fmac_f32_e32 v27, v25, v25
	v_fmac_f32_e32 v23, s10, v236
	v_fmac_f32_e32 v22, s10, v236
	v_add_f32_e32 v26, v26, v27
	v_fmac_f32_e32 v29, s10, v236
	v_fmac_f32_e32 v28, s10, v236
	v_mul_f32_e32 v27, v22, v22
	v_mul_f32_e32 v30, v23, v23
	v_fmac_f32_e32 v27, v28, v28
	v_fmac_f32_e32 v30, v29, v29
	v_add_f32_e32 v27, v27, v30
	v_fmac_f32_e32 v77, s10, v236
	v_fmac_f32_e32 v79, s10, v236
	v_add_f32_e32 v26, v26, v27
	v_fmac_f32_e32 v76, s10, v236
	v_fmac_f32_e32 v78, s10, v236
	v_mul_f32_e32 v27, v79, v79
	v_mul_f32_e32 v30, v77, v77
	v_fmac_f32_e32 v27, v78, v78
	v_fmac_f32_e32 v30, v76, v76
	v_add_f32_e32 v27, v27, v30
	v_fmac_f32_e32 v48, s10, v236
	v_fmac_f32_e32 v50, s10, v236
	v_add_f32_e32 v26, v27, v26
	v_fmac_f32_e32 v44, s10, v236
	v_fmac_f32_e32 v46, s10, v236
	v_mul_f32_e32 v27, v50, v50
	v_mul_f32_e32 v30, v48, v48
	v_fmac_f32_e32 v27, v46, v46
	v_fmac_f32_e32 v30, v44, v44
	v_add_f32_e32 v27, v27, v30
	v_add_f32_e32 v26, v27, v26
	v_mov_b32_e32 v27, v2
	v_mov_b32_e32 v47, v50
	v_add_f32_dpp v26, v26, v26 quad_perm:[1,0,3,2] row_mask:0xf bank_mask:0xf bound_ctrl:1
	v_mov_b32_e32 v45, v48
	s_nop 0
	v_add_f32_dpp v26, v26, v26 quad_perm:[2,3,0,1] row_mask:0xf bank_mask:0xf bound_ctrl:1
	s_nop 1
	v_add_f32_dpp v26, v26, v26 row_half_mirror row_mask:0xf bank_mask:0xf bound_ctrl:1
	s_nop 1
	v_add_f32_dpp v26, v26, v26 row_mirror row_mask:0xf bank_mask:0xf bound_ctrl:1
	s_nop 1
	v_mov_b32_dpp v27, v26 row_bcast:15 row_mask:0xa bank_mask:0xf
	v_add_f32_e32 v26, v26, v27
	v_mov_b32_e32 v27, v2
	s_nop 1
	v_mov_b32_dpp v27, v26 row_bcast:31 row_mask:0xc bank_mask:0xf
	v_add_f32_e32 v26, v26, v27
	s_nop 0
	v_readlane_b32 s10, v26, 63
	s_nop 1
	v_fma_f32 v26, s10, v237, v252
	v_cmp_gt_f32_e32 vcc, s31, v26
	v_mul_f32_e32 v27, 0x4f800000, v26
	s_nop 0
	v_cndmask_b32_e32 v26, v26, v27, vcc
	v_sqrt_f32_e32 v27, v26
	s_nop 0
	v_add_u32_e32 v30, -1, v27
	v_fma_f32 v31, -v30, v27, v26
	v_cmp_ge_f32_e64 s[56:57], 0, v31
	v_add_u32_e32 v31, 1, v27
	s_nop 0
	v_cndmask_b32_e64 v30, v27, v30, s[56:57]
	v_fma_f32 v27, -v31, v27, v26
	v_cmp_lt_f32_e64 s[56:57], 0, v27
	s_nop 1
	v_cndmask_b32_e64 v27, v30, v31, s[56:57]
	v_mul_f32_e32 v30, 0x37800000, v27
	v_cndmask_b32_e32 v27, v27, v30, vcc
	v_cmp_class_f32_e32 vcc, v26, v234
	s_nop 1
	v_cndmask_b32_e32 v26, v27, v26, vcc
	v_div_scale_f32 v27, s[10:11], v26, v26, 1.0
	v_rcp_f32_e32 v30, v27
	s_mov_b64 s[10:11], -1
	v_fma_f32 v31, -v27, v30, 1.0
	v_fmac_f32_e32 v30, v31, v30
	v_div_scale_f32 v31, vcc, 1.0, v26, 1.0
	v_mul_f32_e32 v32, v31, v30
	v_fma_f32 v33, -v27, v32, v31
	v_fmac_f32_e32 v32, v33, v30
	v_fma_f32 v27, -v27, v32, v31
	v_div_fmas_f32 v27, v27, v30, v32
	v_mov_b64_e32 v[30:31], v[108:109]
	v_mov_b64_e32 v[32:33], v[110:111]
	v_mov_b64_e32 v[34:35], v[104:105]
	v_mov_b64_e32 v[36:37], v[106:107]
	v_mov_b64_e32 v[38:39], v[124:125]
	v_mov_b64_e32 v[40:41], v[126:127]
	v_mov_b64_e32 v[82:83], v[120:121]
	v_mov_b64_e32 v[84:85], v[122:123]
	v_div_fixup_f32 v80, v27, v26, 1.0
	v_mov_b32_e32 v27, v20
	v_mov_b32_e32 v20, v25
	v_mov_b32_e32 v26, v24
	v_pk_mul_f32 v[20:21], v[20:21], v[80:81] op_sel_hi:[1,0]
	v_pk_mul_f32 v[42:43], v[26:27], v[80:81] op_sel_hi:[1,0]
	v_pk_mul_f32 v[78:79], v[78:79], v[80:81] op_sel_hi:[1,0]
	v_pk_mul_f32 v[76:77], v[76:77], v[80:81] op_sel_hi:[1,0]
	s_and_b64 vcc, exec, s[54:55]
	s_nop 0
	v_pk_fma_f32 v[26:27], v[36:37], v[20:21], v[84:85]
	v_mov_b32_e32 v20, v28
	v_mov_b32_e32 v21, v22
	v_mov_b32_e32 v22, v29
	v_pk_mul_f32 v[20:21], v[20:21], v[80:81] op_sel_hi:[1,0]
	v_pk_mul_f32 v[22:23], v[22:23], v[80:81] op_sel_hi:[1,0]
	v_pk_fma_f32 v[24:25], v[34:35], v[42:43], v[82:83]
	v_pk_fma_f32 v[22:23], v[32:33], v[22:23], v[40:41]
	v_pk_fma_f32 v[20:21], v[30:31], v[20:21], v[38:39]
	v_mov_b64_e32 v[32:33], v[116:117]
	v_mov_b64_e32 v[34:35], v[118:119]
	v_mov_b64_e32 v[28:29], v[112:113]
	v_mov_b64_e32 v[30:31], v[114:115]
	v_mov_b64_e32 v[36:37], v[132:133]
	v_mov_b64_e32 v[38:39], v[134:135]
	v_mov_b64_e32 v[40:41], v[128:129]
	v_mov_b64_e32 v[42:43], v[130:131]
	s_nop 0
	v_pk_fma_f32 v[30:31], v[30:31], v[76:77], v[42:43]
	v_pk_fma_f32 v[28:29], v[28:29], v[78:79], v[40:41]
	v_pk_mul_f32 v[40:41], v[46:47], v[80:81] op_sel_hi:[1,0]
	v_pk_mul_f32 v[42:43], v[44:45], v[80:81] op_sel_hi:[1,0]
	v_pk_fma_f32 v[32:33], v[32:33], v[40:41], v[36:37]
	v_pk_fma_f32 v[34:35], v[34:35], v[42:43], v[38:39]
	s_cbranch_vccnz .LBB0_1706
	v_lshl_add_u64 v[36:37], s[16:17], 0, v[54:55]
	s_mov_b64 s[10:11], 0
	global_store_dwordx4 v[36:37], v[24:27], off
	global_store_dwordx4 v[36:37], v[20:23], off offset:16
	global_store_dwordx4 v[36:37], v[28:31], off offset:2048
	global_store_dwordx4 v[36:37], v[32:35], off offset:2064
; #define LAS __attribute__((address_space(3)))
; __device__ __forceinline__ float wave_sum(float v) { return rdlane(dpp_sum63(v), 63); }
; __device__ __forceinline__ void row_finalize(CArgs& A, Frame& F, int m, const f32x4 (&v)[4], int Ln) {
;     row_store_bf(WSP(bf16, WS_X) + (size_t)m * D, F.lane, v);
;     const LAS float* wig = (const LAS float*)(F.lds + WIG_OFF); const float* b_in = A.in[10] + (size_t)Ln * DIN + 3072;
;     float r[8];
; #pragma unroll
;     for (int c = 0; c < 8; ++c) { float s = 0.f;
; #pragma unroll
;         for (int j = 0; j < 4; ++j) { const f32x4 w = *(const LAS f32x4*)(wig + c * 1024 + RCOL(F.lane, j)); s += (v[j][0] * w[0] + v[j][1] * w[1]) + (v[j][2] * w[2] + v[j][3] * w[3]); }
;         r[c] = wave_sum(s); if (c & 1) asm volatile("" ::: "memory"); }
.LBB0_1706:
	s_andn2_b64 vcc, exec, s[10:11]
	s_cbranch_vccnz .LBB0_1710
	v_lshl_add_u64 v[40:41], s[58:59], 0, v[72:73]
	s_mov_b32 s10, 0x7680000
	v_add_co_u32_e32 v44, vcc, s10, v40
	v_add_u32_e32 v76, 0, v3
	v_cvt_pk_bf16_f32 v36, v24, v25
	v_cvt_pk_bf16_f32 v37, v26, v27
	v_cvt_pk_bf16_f32 v38, v20, v21
	v_cvt_pk_bf16_f32 v39, v22, v23
	s_nop 0
	v_addc_co_u32_e32 v45, vcc, 0, v41, vcc
	v_add_u32_e32 v46, 0x12000, v76
	global_store_dwordx4 v[44:45], v[36:39], off
	v_add_u32_e32 v48, 0x14000, v76
	s_nop 0
	v_cvt_pk_bf16_f32 v36, v28, v29
	v_cvt_pk_bf16_f32 v37, v30, v31
	v_cvt_pk_bf16_f32 v38, v32, v33
	v_cvt_pk_bf16_f32 v39, v34, v35
	ds_read_b128 v[40:43], v46
	global_store_dwordx4 v[44:45], v[36:39], off offset:1024
	ds_read_b128 v[36:39], v46 offset:16
	s_waitcnt lgkmcnt(1)
	v_mul_f32_e32 v41, v25, v41
	v_fmac_f32_e32 v41, v24, v40
	v_mul_f32_e32 v40, v27, v43
	s_waitcnt lgkmcnt(0)
	v_mul_f32_e32 v37, v21, v37
	v_fmac_f32_e32 v40, v26, v42
	v_fmac_f32_e32 v37, v20, v36
	v_mul_f32_e32 v36, v23, v39
	v_add_f32_e32 v40, v41, v40
	v_fmac_f32_e32 v36, v22, v38
	v_add_f32_e32 v44, 0, v40
	ds_read_b128 v[40:43], v46 offset:2048
	v_add_f32_e32 v36, v37, v36
	v_add_f32_e32 v44, v44, v36
	ds_read_b128 v[36:39], v46 offset:2064
	s_waitcnt lgkmcnt(1)
	v_mul_f32_e32 v41, v29, v41
	v_fmac_f32_e32 v41, v28, v40
	v_mul_f32_e32 v40, v31, v43
	s_waitcnt lgkmcnt(0)
	v_mul_f32_e32 v37, v33, v37
	v_fmac_f32_e32 v40, v30, v42
	v_fmac_f32_e32 v37, v32, v36
	v_mul_f32_e32 v36, v35, v39
	v_add_f32_e32 v40, v41, v40
	v_fmac_f32_e32 v36, v34, v38
	v_add_f32_e32 v40, v44, v40
	v_add_f32_e32 v36, v37, v36
	v_add_f32_e32 v36, v40, v36
	v_mov_b32_e32 v37, v2
	v_add_u32_e32 v44, 0x13000, v76
	v_add_f32_dpp v36, v36, v36 quad_perm:[1,0,3,2] row_mask:0xf bank_mask:0xf bound_ctrl:1
	v_mov_b32_e32 v41, v2
	s_nop 0
	v_add_f32_dpp v36, v36, v36 quad_perm:[2,3,0,1] row_mask:0xf bank_mask:0xf bound_ctrl:1
	s_nop 1
	v_add_f32_dpp v36, v36, v36 row_half_mirror row_mask:0xf bank_mask:0xf bound_ctrl:1
	s_nop 1
	v_add_f32_dpp v36, v36, v36 row_mirror row_mask:0xf bank_mask:0xf bound_ctrl:1
	s_nop 1
	v_mov_b32_dpp v37, v36 row_bcast:15 row_mask:0xa bank_mask:0xf
	v_add_f32_e32 v40, v36, v37
	ds_read_b128 v[36:39], v44
	s_nop 0
	v_mov_b32_dpp v41, v40 row_bcast:31 row_mask:0xc bank_mask:0xf
	v_add_f32_e32 v40, v40, v41
	s_nop 0
	v_readlane_b32 s28, v40, 63
	ds_read_b128 v[40:43], v44 offset:16
	s_waitcnt lgkmcnt(1)
	v_mul_f32_e32 v37, v25, v37
	v_fmac_f32_e32 v37, v24, v36
	v_mul_f32_e32 v36, v27, v39
	v_fmac_f32_e32 v36, v26, v38
	v_add_f32_e32 v36, v37, v36
	s_waitcnt lgkmcnt(0)
	v_mul_f32_e32 v41, v21, v41
	v_add_f32_e32 v45, 0, v36
	v_fmac_f32_e32 v41, v20, v40
	v_mul_f32_e32 v40, v23, v43
	ds_read_b128 v[36:39], v44 offset:2048
	v_fmac_f32_e32 v40, v22, v42
	v_add_f32_e32 v40, v41, v40
	v_add_f32_e32 v45, v45, v40
	ds_read_b128 v[40:43], v44 offset:2064
	s_waitcnt lgkmcnt(1)
	v_mul_f32_e32 v37, v29, v37
	v_fmac_f32_e32 v37, v28, v36
	v_mul_f32_e32 v36, v31, v39
	v_fmac_f32_e32 v36, v30, v38
	v_add_f32_e32 v36, v37, v36
	s_waitcnt lgkmcnt(0)
	v_mul_f32_e32 v37, v33, v41
	v_mul_f32_e32 v38, v35, v43
	v_fmac_f32_e32 v37, v32, v40
	v_fmac_f32_e32 v38, v34, v42
	v_add_f32_e32 v36, v45, v36
	v_add_f32_e32 v37, v37, v38
	v_add_f32_e32 v36, v36, v37
	v_mov_b32_e32 v37, v2
	s_nop 0
	v_add_f32_dpp v36, v36, v36 quad_perm:[1,0,3,2] row_mask:0xf bank_mask:0xf bound_ctrl:1
	s_nop 1
	v_add_f32_dpp v36, v36, v36 quad_perm:[2,3,0,1] row_mask:0xf bank_mask:0xf bound_ctrl:1
	s_nop 1
	v_add_f32_dpp v36, v36, v36 row_half_mirror row_mask:0xf bank_mask:0xf bound_ctrl:1
	s_nop 1
	v_add_f32_dpp v36, v36, v36 row_mirror row_mask:0xf bank_mask:0xf bound_ctrl:1
	s_nop 1
	v_mov_b32_dpp v37, v36 row_bcast:15 row_mask:0xa bank_mask:0xf
	v_add_f32_e32 v36, v36, v37
	v_mov_b32_e32 v37, v2
	s_nop 1
	v_mov_b32_dpp v37, v36 row_bcast:31 row_mask:0xc bank_mask:0xf
	v_add_f32_e32 v40, v36, v37
	ds_read_b128 v[36:39], v48
	v_readlane_b32 s29, v40, 63
	ds_read_b128 v[40:43], v48 offset:2064
	ds_read_b128 v[44:47], v48 offset:2048
	ds_read_b128 v[48:51], v48 offset:16
	s_waitcnt lgkmcnt(3)
	v_mul_f32_e32 v37, v25, v37
	v_fmac_f32_e32 v37, v24, v36
	v_mul_f32_e32 v36, v27, v39
	v_fmac_f32_e32 v36, v26, v38
	v_add_f32_e32 v36, v37, v36
	s_waitcnt lgkmcnt(0)
	v_mul_f32_e32 v37, v21, v49
	v_mul_f32_e32 v38, v23, v51
	v_fmac_f32_e32 v37, v20, v48
	v_fmac_f32_e32 v38, v22, v50
	v_add_f32_e32 v36, 0, v36
	v_add_f32_e32 v37, v37, v38
	v_add_f32_e32 v36, v37, v36
	v_mul_f32_e32 v37, v29, v45
	v_mul_f32_e32 v38, v31, v47
	v_fmac_f32_e32 v37, v28, v44
	v_fmac_f32_e32 v38, v30, v46
	v_add_f32_e32 v37, v37, v38
	v_add_f32_e32 v36, v37, v36
	v_mul_f32_e32 v37, v33, v41
	v_mul_f32_e32 v38, v35, v43
	v_fmac_f32_e32 v37, v32, v40
	v_fmac_f32_e32 v38, v34, v42
	v_add_f32_e32 v37, v37, v38
	v_add_f32_e32 v36, v37, v36
	v_mov_b32_e32 v37, v2
	v_add_u32_e32 v44, 0x15000, v76
	v_add_f32_dpp v36, v36, v36 quad_perm:[1,0,3,2] row_mask:0xf bank_mask:0xf bound_ctrl:1
	v_mov_b32_e32 v41, v2
	v_add_u32_e32 v48, 0x18000, v76
	v_add_f32_dpp v36, v36, v36 quad_perm:[2,3,0,1] row_mask:0xf bank_mask:0xf bound_ctrl:1
	s_nop 1
	v_add_f32_dpp v36, v36, v36 row_half_mirror row_mask:0xf bank_mask:0xf bound_ctrl:1
	s_nop 1
	v_add_f32_dpp v36, v36, v36 row_mirror row_mask:0xf bank_mask:0xf bound_ctrl:1
	s_nop 1
	v_mov_b32_dpp v37, v36 row_bcast:15 row_mask:0xa bank_mask:0xf
	v_add_f32_e32 v40, v36, v37
	ds_read_b128 v[36:39], v44
	s_nop 0
	v_mov_b32_dpp v41, v40 row_bcast:31 row_mask:0xc bank_mask:0xf
	v_add_f32_e32 v40, v40, v41
	s_nop 0
	v_readlane_b32 s36, v40, 63
	ds_read_b128 v[40:43], v44 offset:16
	s_waitcnt lgkmcnt(1)
; #define LAS __attribute__((address_space(3)))
; __device__ __forceinline__ float wave_sum(float v) { return rdlane(dpp_sum63(v), 63); }
; __device__ __forceinline__ void row_finalize(CArgs& A, Frame& F, int m, const f32x4 (&v)[4], int Ln) {
;     ...
;     for (int c = 0; c < 8; ++c) { float s = 0.f;
; #pragma unroll
;         for (int j = 0; j < 4; ++j) { const f32x4 w = *(const LAS f32x4*)(wig + c * 1024 + RCOL(F.lane, j)); s += (v[j][0] * w[0] + v[j][1] * w[1]) + (v[j][2] * w[2] + v[j][3] * w[3]); }
;         r[c] = wave_sum(s); if (c & 1) asm volatile("" ::: "memory"); }
	v_mul_f32_e32 v37, v25, v37
	v_fmac_f32_e32 v37, v24, v36
	v_mul_f32_e32 v36, v27, v39
	v_fmac_f32_e32 v36, v26, v38
	v_add_f32_e32 v36, v37, v36
	s_waitcnt lgkmcnt(0)
	v_mul_f32_e32 v41, v21, v41
	v_add_f32_e32 v45, 0, v36
	v_fmac_f32_e32 v41, v20, v40
	v_mul_f32_e32 v40, v23, v43
	ds_read_b128 v[36:39], v44 offset:2048
	v_fmac_f32_e32 v40, v22, v42
	v_add_f32_e32 v40, v41, v40
	v_add_f32_e32 v45, v45, v40
	ds_read_b128 v[40:43], v44 offset:2064
	s_waitcnt lgkmcnt(1)
	v_mul_f32_e32 v37, v29, v37
	v_fmac_f32_e32 v37, v28, v36
	v_mul_f32_e32 v36, v31, v39
	v_fmac_f32_e32 v36, v30, v38
	v_add_f32_e32 v36, v37, v36
	s_waitcnt lgkmcnt(0)
	v_mul_f32_e32 v37, v33, v41
	v_mul_f32_e32 v38, v35, v43
	v_fmac_f32_e32 v37, v32, v40
	v_fmac_f32_e32 v38, v34, v42
	v_add_f32_e32 v36, v45, v36
	v_add_f32_e32 v37, v37, v38
	v_add_f32_e32 v36, v36, v37
	v_mov_b32_e32 v37, v2
	v_add_u32_e32 v44, 0x16000, v76
	v_add_f32_dpp v36, v36, v36 quad_perm:[1,0,3,2] row_mask:0xf bank_mask:0xf bound_ctrl:1
	v_mov_b32_e32 v41, v2
	s_nop 0
	v_add_f32_dpp v36, v36, v36 quad_perm:[2,3,0,1] row_mask:0xf bank_mask:0xf bound_ctrl:1
	s_nop 1
	v_add_f32_dpp v36, v36, v36 row_half_mirror row_mask:0xf bank_mask:0xf bound_ctrl:1
	s_nop 1
	v_add_f32_dpp v36, v36, v36 row_mirror row_mask:0xf bank_mask:0xf bound_ctrl:1
	s_nop 1
	v_mov_b32_dpp v37, v36 row_bcast:15 row_mask:0xa bank_mask:0xf
	v_add_f32_e32 v40, v36, v37
	ds_read_b128 v[36:39], v44
	s_nop 0
	v_mov_b32_dpp v41, v40 row_bcast:31 row_mask:0xc bank_mask:0xf
	v_add_f32_e32 v40, v40, v41
	s_nop 0
	v_readlane_b32 s37, v40, 63
	ds_read_b128 v[40:43], v44 offset:16
	s_waitcnt lgkmcnt(1)
	v_mul_f32_e32 v37, v25, v37
	v_fmac_f32_e32 v37, v24, v36
	v_mul_f32_e32 v36, v27, v39
	v_fmac_f32_e32 v36, v26, v38
	v_add_f32_e32 v36, v37, v36
	s_waitcnt lgkmcnt(0)
	v_mul_f32_e32 v41, v21, v41
	v_add_f32_e32 v45, 0, v36
	v_fmac_f32_e32 v41, v20, v40
	v_mul_f32_e32 v40, v23, v43
	ds_read_b128 v[36:39], v44 offset:2048
	v_fmac_f32_e32 v40, v22, v42
	v_add_f32_e32 v40, v41, v40
	v_add_f32_e32 v45, v45, v40
	ds_read_b128 v[40:43], v44 offset:2064
	s_waitcnt lgkmcnt(1)
	v_mul_f32_e32 v37, v29, v37
	v_fmac_f32_e32 v37, v28, v36
	v_mul_f32_e32 v36, v31, v39
	v_fmac_f32_e32 v36, v30, v38
	v_add_f32_e32 v36, v37, v36
	s_waitcnt lgkmcnt(0)
	v_mul_f32_e32 v37, v33, v41
	v_mul_f32_e32 v38, v35, v43
	v_fmac_f32_e32 v37, v32, v40
	v_fmac_f32_e32 v38, v34, v42
	v_add_f32_e32 v36, v45, v36
	v_add_f32_e32 v37, v37, v38
	v_add_f32_e32 v36, v36, v37
	v_mov_b32_e32 v37, v2
	v_add_u32_e32 v44, 0x17000, v76
	v_add_f32_dpp v36, v36, v36 quad_perm:[1,0,3,2] row_mask:0xf bank_mask:0xf bound_ctrl:1
	v_mov_b32_e32 v41, v2
	s_nop 0
	v_add_f32_dpp v36, v36, v36 quad_perm:[2,3,0,1] row_mask:0xf bank_mask:0xf bound_ctrl:1
	s_nop 1
	v_add_f32_dpp v36, v36, v36 row_half_mirror row_mask:0xf bank_mask:0xf bound_ctrl:1
	s_nop 1
	v_add_f32_dpp v36, v36, v36 row_mirror row_mask:0xf bank_mask:0xf bound_ctrl:1
	s_nop 1
	v_mov_b32_dpp v37, v36 row_bcast:15 row_mask:0xa bank_mask:0xf
	v_add_f32_e32 v40, v36, v37
	ds_read_b128 v[36:39], v44
	s_nop 0
	v_mov_b32_dpp v41, v40 row_bcast:31 row_mask:0xc bank_mask:0xf
	v_add_f32_e32 v40, v40, v41
	s_nop 0
	v_readlane_b32 s56, v40, 63
	ds_read_b128 v[40:43], v44 offset:16
	s_waitcnt lgkmcnt(1)
	v_mul_f32_e32 v37, v25, v37
	v_fmac_f32_e32 v37, v24, v36
	v_mul_f32_e32 v36, v27, v39
	v_fmac_f32_e32 v36, v26, v38
	v_add_f32_e32 v36, v37, v36
	s_waitcnt lgkmcnt(0)
	v_mul_f32_e32 v41, v21, v41
	v_add_f32_e32 v45, 0, v36
	v_fmac_f32_e32 v41, v20, v40
	v_mul_f32_e32 v40, v23, v43
	ds_read_b128 v[36:39], v44 offset:2048
	v_fmac_f32_e32 v40, v22, v42
	v_add_f32_e32 v40, v41, v40
	v_add_f32_e32 v45, v45, v40
	ds_read_b128 v[40:43], v44 offset:2064
	s_waitcnt lgkmcnt(1)
	v_mul_f32_e32 v37, v29, v37
	v_fmac_f32_e32 v37, v28, v36
	v_mul_f32_e32 v36, v31, v39
	v_fmac_f32_e32 v36, v30, v38
	v_add_f32_e32 v36, v37, v36
	s_waitcnt lgkmcnt(0)
	v_mul_f32_e32 v37, v33, v41
	v_mul_f32_e32 v38, v35, v43
	v_fmac_f32_e32 v37, v32, v40
	v_fmac_f32_e32 v38, v34, v42
	v_add_f32_e32 v36, v45, v36
	v_add_f32_e32 v37, v37, v38
	v_add_f32_e32 v36, v36, v37
	v_mov_b32_e32 v37, v2
	s_nop 0
	v_add_f32_dpp v36, v36, v36 quad_perm:[1,0,3,2] row_mask:0xf bank_mask:0xf bound_ctrl:1
	s_nop 1
	v_add_f32_dpp v36, v36, v36 quad_perm:[2,3,0,1] row_mask:0xf bank_mask:0xf bound_ctrl:1
	s_nop 1
	v_add_f32_dpp v36, v36, v36 row_half_mirror row_mask:0xf bank_mask:0xf bound_ctrl:1
	s_nop 1
	v_add_f32_dpp v36, v36, v36 row_mirror row_mask:0xf bank_mask:0xf bound_ctrl:1
	s_nop 1
	v_mov_b32_dpp v37, v36 row_bcast:15 row_mask:0xa bank_mask:0xf
	v_add_f32_e32 v36, v36, v37
	v_mov_b32_e32 v37, v2
	s_nop 1
	v_mov_b32_dpp v37, v36 row_bcast:31 row_mask:0xc bank_mask:0xf
	v_add_f32_e32 v40, v36, v37
	ds_read_b128 v[36:39], v48
	v_readlane_b32 s57, v40, 63
	ds_read_b128 v[40:43], v48 offset:2064
	ds_read_b128 v[44:47], v48 offset:2048
	ds_read_b128 v[48:51], v48 offset:16
	s_waitcnt lgkmcnt(3)
; #define LAS __attribute__((address_space(3)))
; __device__ __forceinline__ float wave_sum(float v) { return rdlane(dpp_sum63(v), 63); }
; __device__ __forceinline__ void row_finalize(CArgs& A, Frame& F, int m, const f32x4 (&v)[4], int Ln) {
;     ...
;     for (int c = 0; c < 8; ++c) { float s = 0.f;
; #pragma unroll
;         for (int j = 0; j < 4; ++j) { const f32x4 w = *(const LAS f32x4*)(wig + c * 1024 + RCOL(F.lane, j)); s += (v[j][0] * w[0] + v[j][1] * w[1]) + (v[j][2] * w[2] + v[j][3] * w[3]); }
;         r[c] = wave_sum(s); if (c & 1) asm volatile("" ::: "memory"); }
;     if (F.lane < 8) { float x = r[0];
; #pragma unroll
;         for (int c = 1; c < 8; ++c) x = (F.lane == c) ? r[c] : x;
;         WSP(float, WS_IGFG)[(size_t)m * 8 + F.lane] = x + b_in[F.lane]; }
	v_mul_f32_e32 v37, v25, v37
	v_fmac_f32_e32 v37, v24, v36
	v_mul_f32_e32 v36, v27, v39
	v_fmac_f32_e32 v36, v26, v38
	v_add_f32_e32 v36, v37, v36
	s_waitcnt lgkmcnt(0)
	v_mul_f32_e32 v37, v21, v49
	v_mul_f32_e32 v38, v23, v51
	v_fmac_f32_e32 v37, v20, v48
	v_fmac_f32_e32 v38, v22, v50
	v_add_f32_e32 v36, 0, v36
	v_add_f32_e32 v37, v37, v38
	v_add_f32_e32 v36, v37, v36
	v_mul_f32_e32 v37, v29, v45
	v_mul_f32_e32 v38, v31, v47
	v_fmac_f32_e32 v37, v28, v44
	v_fmac_f32_e32 v38, v30, v46
	v_add_f32_e32 v37, v37, v38
	v_add_f32_e32 v36, v37, v36
	v_mul_f32_e32 v37, v33, v41
	v_mul_f32_e32 v38, v35, v43
	v_fmac_f32_e32 v37, v32, v40
	v_fmac_f32_e32 v38, v34, v42
	v_add_f32_e32 v37, v37, v38
	v_add_f32_e32 v36, v37, v36
	v_mov_b32_e32 v37, v2
	v_mov_b32_e32 v41, v2
	v_add_f32_dpp v36, v36, v36 quad_perm:[1,0,3,2] row_mask:0xf bank_mask:0xf bound_ctrl:1
	v_add_u32_e32 v44, 0x19000, v76
	s_nop 0
	v_add_f32_dpp v36, v36, v36 quad_perm:[2,3,0,1] row_mask:0xf bank_mask:0xf bound_ctrl:1
	s_nop 1
	v_add_f32_dpp v36, v36, v36 row_half_mirror row_mask:0xf bank_mask:0xf bound_ctrl:1
	s_nop 1
	v_add_f32_dpp v36, v36, v36 row_mirror row_mask:0xf bank_mask:0xf bound_ctrl:1
	s_nop 1
	v_mov_b32_dpp v37, v36 row_bcast:15 row_mask:0xa bank_mask:0xf
	v_add_f32_e32 v40, v36, v37
	ds_read_b128 v[36:39], v44
	s_nop 0
	v_mov_b32_dpp v41, v40 row_bcast:31 row_mask:0xc bank_mask:0xf
	v_add_f32_e32 v40, v40, v41
	s_nop 0
	v_readlane_b32 s60, v40, 63
	ds_read_b128 v[40:43], v44 offset:16
	s_waitcnt lgkmcnt(1)
	v_mul_f32_e32 v25, v25, v37
	v_fmac_f32_e32 v25, v24, v36
	v_mul_f32_e32 v24, v27, v39
	v_fmac_f32_e32 v24, v26, v38
	s_waitcnt lgkmcnt(0)
	v_mul_f32_e32 v21, v21, v41
	v_fmac_f32_e32 v21, v20, v40
	v_mul_f32_e32 v20, v23, v43
	v_add_f32_e32 v24, v25, v24
	v_fmac_f32_e32 v20, v22, v42
	v_add_f32_e32 v36, 0, v24
	ds_read_b128 v[24:27], v44 offset:2048
	v_add_f32_e32 v20, v21, v20
	v_add_f32_e32 v36, v36, v20
	ds_read_b128 v[20:23], v44 offset:2064
	s_waitcnt lgkmcnt(1)
	v_mul_f32_e32 v25, v29, v25
	v_fmac_f32_e32 v25, v28, v24
	v_mul_f32_e32 v24, v31, v27
	s_waitcnt lgkmcnt(0)
	v_mul_f32_e32 v21, v33, v21
	v_fmac_f32_e32 v24, v30, v26
	v_fmac_f32_e32 v21, v32, v20
	v_mul_f32_e32 v20, v35, v23
	v_add_f32_e32 v24, v25, v24
	v_fmac_f32_e32 v20, v34, v22
	v_add_f32_e32 v24, v36, v24
	v_add_f32_e32 v20, v21, v20
	v_add_f32_e32 v20, v24, v20
	v_mov_b32_e32 v21, v2
	s_nop 0
	v_add_f32_dpp v20, v20, v20 quad_perm:[1,0,3,2] row_mask:0xf bank_mask:0xf bound_ctrl:1
	s_nop 1
	v_add_f32_dpp v20, v20, v20 quad_perm:[2,3,0,1] row_mask:0xf bank_mask:0xf bound_ctrl:1
	s_nop 1
	v_add_f32_dpp v20, v20, v20 row_half_mirror row_mask:0xf bank_mask:0xf bound_ctrl:1
	s_nop 1
	v_add_f32_dpp v20, v20, v20 row_mirror row_mask:0xf bank_mask:0xf bound_ctrl:1
	s_nop 1
	v_mov_b32_dpp v21, v20 row_bcast:15 row_mask:0xa bank_mask:0xf
	v_add_f32_e32 v20, v20, v21
	v_mov_b32_e32 v21, v2
	s_nop 1
	v_mov_b32_dpp v21, v20 row_bcast:31 row_mask:0xc bank_mask:0xf
	v_add_f32_e32 v20, v20, v21
	s_nop 0
	v_readlane_b32 s61, v20, 63
	s_and_saveexec_b64 s[10:11], s[38:39]
	s_cbranch_execz .LBB0_1709
	s_load_dwordx2 s[64:65], s[2:3], 0x50
	v_mov_b32_e32 v20, s28
	v_mov_b32_e32 v21, s29
	v_cndmask_b32_e64 v20, v20, v21, s[40:41]
	v_mov_b32_e32 v21, s36
	v_cndmask_b32_e64 v20, v20, v21, s[42:43]
	v_mov_b32_e32 v21, s37
	v_cndmask_b32_e64 v20, v20, v21, s[44:45]
	v_mov_b32_e32 v21, s56
	v_cndmask_b32_e64 v20, v20, v21, s[46:47]
	v_mov_b32_e32 v21, s57
	s_waitcnt lgkmcnt(0)
	s_add_u32 s64, s64, s26
	v_cndmask_b32_e64 v20, v20, v21, s[48:49]
	v_mov_b32_e32 v21, s60
	s_addc_u32 s65, s65, s13
	v_cndmask_b32_e64 v20, v20, v21, s[50:51]
	v_mov_b32_e32 v21, s61
	v_cndmask_b32_e64 v22, v20, v21, s[52:53]
	v_lshl_add_u64 v[20:21], v[0:1], 2, s[64:65]
	v_add_co_u32_e32 v20, vcc, 0x3000, v20
	s_nop 1
	v_addc_co_u32_e32 v21, vcc, 0, v21, vcc
	v_mov_b32_e32 v20, v168
	s_nop 0
	v_add_f32_e32 v22, v22, v20
	v_lshl_add_u64 v[20:21], s[58:59], 0, v[74:75]
	global_store_dword v[20:21], v22, off

; __device__ __forceinline__ float bflo(unsigned w) { return __uint_as_float(w << 16); }
; __device__ __forceinline__ float bfhi(unsigned w) { return __uint_as_float(w & 0xffff0000u); }
; __device__ __forceinline__ float wave_sum(float v) { return rdlane(dpp_sum63(v), 63); }
; __device__ __forceinline__ void row_unpack(const u32x4 (&r)[2], f32x4 (&v)[4]) {
; #pragma unroll
;     for (int j = 0; j < 2; ++j) { v[2 * j] = (f32x4){bflo(r[j].x), bfhi(r[j].x), bflo(r[j].y), bfhi(r[j].y)}; v[2 * j + 1] = (f32x4){bflo(r[j].z), bfhi(r[j].z), bflo(r[j].w), bfhi(r[j].w)}; }
; }
; __device__ __forceinline__ void row_ln(f32x4 (&v)[4], const float* g, const float* b, int lane) {
;     float s = 0.f;
; #pragma unroll
;     for (int j = 0; j < 4; ++j) s += (v[j][0] + v[j][1]) + (v[j][2] + v[j][3]);
;     const float mean = wave_sum(s) * (1.f / D); float s2 = 0.f;
; #pragma unroll
;     for (int j = 0; j < 4; ++j) { v[j] = v[j] - mean; s2 += (v[j][0] * v[j][0] + v[j][1] * v[j][1]) + (v[j][2] * v[j][2] + v[j][3] * v[j][3]); }
;     const float rstd = 1.0f / sqrtf(wave_sum(s2) * (1.f / D) + LN_EPS);
; #pragma unroll
;     for (int j = 0; j < 4; ++j) { const f32x4 gg = *(const f32x4*)(g + RCOL(lane, j)), bb = *(const f32x4*)(b + RCOL(lane, j)); v[j] = v[j] * rstd * gg + bb; }
.LBB0_1710:
	s_cmp_ge_i32 s27, s8
	s_cbranch_scc1 .LBB0_1717
	v_lshlrev_b32_e32 v46, 16, v16
	v_and_b32_e32 v47, 0xffff0000, v16
	v_lshlrev_b32_e32 v44, 16, v17
	v_and_b32_e32 v45, 0xffff0000, v17
	v_lshlrev_b32_e32 v17, 16, v13
	v_lshlrev_b32_e32 v16, 16, v12
	v_and_b32_e32 v13, 0xffff0000, v13
	v_and_b32_e32 v12, 0xffff0000, v12
	v_lshlrev_b32_e32 v38, 16, v18
	v_and_b32_e32 v42, 0xffff0000, v18
	v_lshlrev_b32_e32 v36, 16, v19
	v_and_b32_e32 v40, 0xffff0000, v19
	v_pk_add_f32 v[18:19], v[16:17], v[12:13]
	v_lshlrev_b32_e32 v21, 16, v15
	v_add_f32_e32 v18, v18, v19
	v_lshlrev_b32_e32 v20, 16, v14
	v_and_b32_e32 v15, 0xffff0000, v15
	v_and_b32_e32 v14, 0xffff0000, v14
	v_add_f32_e32 v41, 0, v18
	v_pk_add_f32 v[18:19], v[20:21], v[14:15]
	v_add_f32_e32 v39, v46, v47
	v_pk_add_f32 v[18:19], v[18:19], v[18:19] op_sel_hi:[0,1]
	v_add_f32_e32 v43, v44, v45
	v_mov_b32_e32 v37, v19
	v_pk_add_f32 v[22:23], v[38:39], v[42:43]
	v_pk_add_f32 v[18:19], v[36:37], v[40:41]
	s_nop 0
	v_pk_add_f32 v[18:19], v[22:23], v[18:19]
	s_nop 0
	v_add_f32_e32 v18, v18, v19
	v_mov_b32_e32 v19, v2
	s_nop 0
	v_add_f32_dpp v18, v18, v18 quad_perm:[1,0,3,2] row_mask:0xf bank_mask:0xf bound_ctrl:1
	s_nop 1
	v_add_f32_dpp v18, v18, v18 quad_perm:[2,3,0,1] row_mask:0xf bank_mask:0xf bound_ctrl:1
	s_nop 1
	v_add_f32_dpp v18, v18, v18 row_half_mirror row_mask:0xf bank_mask:0xf bound_ctrl:1
	s_nop 1
	v_add_f32_dpp v18, v18, v18 row_mirror row_mask:0xf bank_mask:0xf bound_ctrl:1
	s_nop 1
	v_mov_b32_dpp v19, v18 row_bcast:15 row_mask:0xa bank_mask:0xf
	v_add_f32_e32 v18, v18, v19
	v_mov_b32_e32 v19, v2
	s_nop 1
	v_mov_b32_dpp v19, v18 row_bcast:31 row_mask:0xc bank_mask:0xf
	v_add_f32_e32 v18, v18, v19
	s_nop 0
	v_readlane_b32 s10, v18, 63
	s_nop 1
	v_fmac_f32_e32 v13, s10, v236
	v_fmac_f32_e32 v12, s10, v236
	v_fmac_f32_e32 v17, s10, v236
	v_fmac_f32_e32 v16, s10, v236
	v_mul_f32_e32 v18, v12, v12
	v_mul_f32_e32 v19, v13, v13
	v_fmac_f32_e32 v18, v16, v16
	v_fmac_f32_e32 v19, v17, v17
	v_fmac_f32_e32 v15, s10, v236
	v_fmac_f32_e32 v14, s10, v236
	v_add_f32_e32 v18, v18, v19
	v_fmac_f32_e32 v21, s10, v236
	v_fmac_f32_e32 v20, s10, v236
	v_mul_f32_e32 v19, v14, v14
	v_mul_f32_e32 v22, v15, v15
	v_fmac_f32_e32 v19, v20, v20
	v_fmac_f32_e32 v22, v21, v21
	v_add_f32_e32 v19, v19, v22
	v_fmac_f32_e32 v45, s10, v236
	v_fmac_f32_e32 v47, s10, v236
	v_add_f32_e32 v18, v18, v19
	v_fmac_f32_e32 v44, s10, v236
	v_fmac_f32_e32 v46, s10, v236
	v_mul_f32_e32 v19, v47, v47
	v_mul_f32_e32 v22, v45, v45
	v_fmac_f32_e32 v19, v46, v46
	v_fmac_f32_e32 v22, v44, v44
	v_add_f32_e32 v19, v19, v22
	v_fmac_f32_e32 v40, s10, v236
	v_fmac_f32_e32 v42, s10, v236
	v_add_f32_e32 v18, v19, v18
	v_fmac_f32_e32 v36, s10, v236
	v_fmac_f32_e32 v38, s10, v236
	v_mul_f32_e32 v19, v42, v42
	v_mul_f32_e32 v22, v40, v40
	v_fmac_f32_e32 v19, v38, v38
	v_fmac_f32_e32 v22, v36, v36
	v_add_f32_e32 v19, v19, v22
	v_add_f32_e32 v18, v19, v18
	v_mov_b32_e32 v19, v2
	v_mov_b32_e32 v39, v42
	v_add_f32_dpp v18, v18, v18 quad_perm:[1,0,3,2] row_mask:0xf bank_mask:0xf bound_ctrl:1
	v_mov_b32_e32 v37, v40
	s_nop 0
	v_add_f32_dpp v18, v18, v18 quad_perm:[2,3,0,1] row_mask:0xf bank_mask:0xf bound_ctrl:1
	s_nop 1
	v_add_f32_dpp v18, v18, v18 row_half_mirror row_mask:0xf bank_mask:0xf bound_ctrl:1
	s_nop 1
	v_add_f32_dpp v18, v18, v18 row_mirror row_mask:0xf bank_mask:0xf bound_ctrl:1
	s_nop 1
	v_mov_b32_dpp v19, v18 row_bcast:15 row_mask:0xa bank_mask:0xf
	v_add_f32_e32 v18, v18, v19
	v_mov_b32_e32 v19, v2
	s_nop 1
	v_mov_b32_dpp v19, v18 row_bcast:31 row_mask:0xc bank_mask:0xf
	v_add_f32_e32 v18, v18, v19
	s_nop 0
	v_readlane_b32 s10, v18, 63
	s_nop 1
	v_fma_f32 v18, s10, v237, v252
	v_cmp_gt_f32_e32 vcc, s31, v18
	v_mul_f32_e32 v19, 0x4f800000, v18
	s_nop 0
	v_cndmask_b32_e32 v18, v18, v19, vcc
	v_sqrt_f32_e32 v19, v18
	s_nop 0
	v_add_u32_e32 v22, -1, v19
	v_fma_f32 v23, -v22, v19, v18
	v_cmp_ge_f32_e64 s[56:57], 0, v23
	v_add_u32_e32 v23, 1, v19
	s_nop 0
	v_cndmask_b32_e64 v22, v19, v22, s[56:57]
	v_fma_f32 v19, -v23, v19, v18
	v_cmp_lt_f32_e64 s[56:57], 0, v19
	s_nop 1
	v_cndmask_b32_e64 v19, v22, v23, s[56:57]
	v_mul_f32_e32 v22, 0x37800000, v19
	v_cndmask_b32_e32 v19, v19, v22, vcc
	v_cmp_class_f32_e32 vcc, v18, v234
	s_nop 1
	v_cndmask_b32_e32 v18, v19, v18, vcc
	v_div_scale_f32 v19, s[10:11], v18, v18, 1.0
	v_rcp_f32_e32 v22, v19
	s_mov_b64 s[10:11], -1
	v_fma_f32 v23, -v19, v22, 1.0
	v_fmac_f32_e32 v22, v23, v22
	v_div_scale_f32 v23, vcc, 1.0, v18, 1.0
	v_mul_f32_e32 v24, v23, v22
	v_fma_f32 v25, -v19, v24, v23
	v_fmac_f32_e32 v24, v25, v22
	v_fma_f32 v19, -v19, v24, v23
	v_div_fmas_f32 v19, v19, v22, v24
	v_mov_b64_e32 v[22:23], v[108:109]
	v_mov_b64_e32 v[24:25], v[110:111]
	v_mov_b64_e32 v[26:27], v[104:105]
	v_mov_b64_e32 v[28:29], v[106:107]
	v_mov_b64_e32 v[30:31], v[124:125]
	v_mov_b64_e32 v[32:33], v[126:127]
	v_mov_b64_e32 v[76:77], v[120:121]
	v_mov_b64_e32 v[78:79], v[122:123]
	v_div_fixup_f32 v48, v19, v18, 1.0
	v_mov_b32_e32 v19, v12
	v_mov_b32_e32 v12, v17
	v_mov_b32_e32 v18, v16
	v_pk_mul_f32 v[12:13], v[12:13], v[48:49] op_sel_hi:[1,0]
	v_pk_mul_f32 v[34:35], v[18:19], v[48:49] op_sel_hi:[1,0]
	v_pk_mul_f32 v[46:47], v[46:47], v[48:49] op_sel_hi:[1,0]
	v_pk_mul_f32 v[44:45], v[44:45], v[48:49] op_sel_hi:[1,0]
	s_and_b64 vcc, exec, s[54:55]
	s_nop 0
	v_pk_fma_f32 v[18:19], v[28:29], v[12:13], v[78:79]
	v_mov_b32_e32 v12, v20
	v_mov_b32_e32 v13, v14
	v_mov_b32_e32 v14, v21
	v_pk_mul_f32 v[12:13], v[12:13], v[48:49] op_sel_hi:[1,0]
	v_pk_mul_f32 v[14:15], v[14:15], v[48:49] op_sel_hi:[1,0]
	v_pk_fma_f32 v[16:17], v[26:27], v[34:35], v[76:77]
	v_pk_fma_f32 v[14:15], v[24:25], v[14:15], v[32:33]
	v_pk_fma_f32 v[12:13], v[22:23], v[12:13], v[30:31]
	v_mov_b64_e32 v[24:25], v[116:117]
	v_mov_b64_e32 v[26:27], v[118:119]
	v_mov_b64_e32 v[20:21], v[112:113]
	v_mov_b64_e32 v[22:23], v[114:115]
	v_mov_b64_e32 v[28:29], v[132:133]
	v_mov_b64_e32 v[30:31], v[134:135]
	v_mov_b64_e32 v[32:33], v[128:129]
	v_mov_b64_e32 v[34:35], v[130:131]
	s_nop 0
	v_pk_fma_f32 v[22:23], v[22:23], v[44:45], v[34:35]
	v_pk_fma_f32 v[20:21], v[20:21], v[46:47], v[32:33]
	v_pk_mul_f32 v[32:33], v[38:39], v[48:49] op_sel_hi:[1,0]
	v_pk_mul_f32 v[34:35], v[36:37], v[48:49] op_sel_hi:[1,0]
	v_pk_fma_f32 v[24:25], v[24:25], v[32:33], v[28:29]
	v_pk_fma_f32 v[26:27], v[26:27], v[34:35], v[30:31]
	s_cbranch_vccnz .LBB0_1713
	v_lshl_add_u64 v[28:29], s[34:35], 0, v[54:55]
	s_mov_b64 s[10:11], 0
	global_store_dwordx4 v[28:29], v[16:19], off
	global_store_dwordx4 v[28:29], v[12:15], off offset:16
	global_store_dwordx4 v[28:29], v[20:23], off offset:2048
	global_store_dwordx4 v[28:29], v[24:27], off offset:2064
; #define LAS __attribute__((address_space(3)))
; __device__ __forceinline__ float wave_sum(float v) { return rdlane(dpp_sum63(v), 63); }
; __device__ __forceinline__ void row_finalize(CArgs& A, Frame& F, int m, const f32x4 (&v)[4], int Ln) {
;     row_store_bf(WSP(bf16, WS_X) + (size_t)m * D, F.lane, v);
;     const LAS float* wig = (const LAS float*)(F.lds + WIG_OFF); const float* b_in = A.in[10] + (size_t)Ln * DIN + 3072;
;     float r[8];
; #pragma unroll
;     for (int c = 0; c < 8; ++c) { float s = 0.f;
; #pragma unroll
;         for (int j = 0; j < 4; ++j) { const f32x4 w = *(const LAS f32x4*)(wig + c * 1024 + RCOL(F.lane, j)); s += (v[j][0] * w[0] + v[j][1] * w[1]) + (v[j][2] * w[2] + v[j][3] * w[3]); }
;         r[c] = wave_sum(s); if (c & 1) asm volatile("" ::: "memory"); }
.LBB0_1713:
	s_andn2_b64 vcc, exec, s[10:11]
	s_cbranch_vccnz .LBB0_1717
	v_lshl_add_u64 v[32:33], s[58:59], 0, v[70:71]
	s_mov_b32 s10, 0x7680000
	v_add_co_u32_e32 v36, vcc, s10, v32
	v_add_u32_e32 v44, 0, v3
	v_cvt_pk_bf16_f32 v28, v16, v17
	v_cvt_pk_bf16_f32 v29, v18, v19
	v_cvt_pk_bf16_f32 v30, v12, v13
	v_cvt_pk_bf16_f32 v31, v14, v15
	s_nop 0
	v_addc_co_u32_e32 v37, vcc, 0, v33, vcc
	v_add_u32_e32 v38, 0x12000, v44
	global_store_dwordx4 v[36:37], v[28:31], off
	v_add_u32_e32 v40, 0x14000, v44
	s_nop 0
	v_cvt_pk_bf16_f32 v28, v20, v21
	v_cvt_pk_bf16_f32 v29, v22, v23
	v_cvt_pk_bf16_f32 v30, v24, v25
	v_cvt_pk_bf16_f32 v31, v26, v27
	ds_read_b128 v[32:35], v38
	global_store_dwordx4 v[36:37], v[28:31], off offset:1024
	ds_read_b128 v[28:31], v38 offset:16
	s_waitcnt lgkmcnt(1)
	v_mul_f32_e32 v33, v17, v33
	v_fmac_f32_e32 v33, v16, v32
	v_mul_f32_e32 v32, v19, v35
	s_waitcnt lgkmcnt(0)
	v_mul_f32_e32 v29, v13, v29
	v_fmac_f32_e32 v32, v18, v34
	v_fmac_f32_e32 v29, v12, v28
	v_mul_f32_e32 v28, v15, v31
	v_add_f32_e32 v32, v33, v32
	v_fmac_f32_e32 v28, v14, v30
	v_add_f32_e32 v36, 0, v32
	ds_read_b128 v[32:35], v38 offset:2048
	v_add_f32_e32 v28, v29, v28
	v_add_f32_e32 v36, v36, v28
	ds_read_b128 v[28:31], v38 offset:2064
	s_waitcnt lgkmcnt(1)
	v_mul_f32_e32 v33, v21, v33
	v_fmac_f32_e32 v33, v20, v32
	v_mul_f32_e32 v32, v23, v35
	s_waitcnt lgkmcnt(0)
	v_mul_f32_e32 v29, v25, v29
	v_fmac_f32_e32 v32, v22, v34
	v_fmac_f32_e32 v29, v24, v28
	v_mul_f32_e32 v28, v27, v31
	v_add_f32_e32 v32, v33, v32
	v_fmac_f32_e32 v28, v26, v30
	v_add_f32_e32 v32, v36, v32
	v_add_f32_e32 v28, v29, v28
	v_add_f32_e32 v28, v32, v28
	v_mov_b32_e32 v29, v2
	v_add_u32_e32 v36, 0x13000, v44
	v_add_f32_dpp v28, v28, v28 quad_perm:[1,0,3,2] row_mask:0xf bank_mask:0xf bound_ctrl:1
	v_mov_b32_e32 v33, v2
	s_nop 0
	v_add_f32_dpp v28, v28, v28 quad_perm:[2,3,0,1] row_mask:0xf bank_mask:0xf bound_ctrl:1
	s_nop 1
	v_add_f32_dpp v28, v28, v28 row_half_mirror row_mask:0xf bank_mask:0xf bound_ctrl:1
	s_nop 1
	v_add_f32_dpp v28, v28, v28 row_mirror row_mask:0xf bank_mask:0xf bound_ctrl:1
	s_nop 1
	v_mov_b32_dpp v29, v28 row_bcast:15 row_mask:0xa bank_mask:0xf
	v_add_f32_e32 v32, v28, v29
	ds_read_b128 v[28:31], v36
	s_nop 0
	v_mov_b32_dpp v33, v32 row_bcast:31 row_mask:0xc bank_mask:0xf
	v_add_f32_e32 v32, v32, v33
	s_nop 0
	v_readlane_b32 s27, v32, 63
	ds_read_b128 v[32:35], v36 offset:16
	s_waitcnt lgkmcnt(1)
	v_mul_f32_e32 v29, v17, v29
	v_fmac_f32_e32 v29, v16, v28
	v_mul_f32_e32 v28, v19, v31
	v_fmac_f32_e32 v28, v18, v30
	v_add_f32_e32 v28, v29, v28
	s_waitcnt lgkmcnt(0)
	v_mul_f32_e32 v33, v13, v33
	v_add_f32_e32 v37, 0, v28
	v_fmac_f32_e32 v33, v12, v32
	v_mul_f32_e32 v32, v15, v35
	ds_read_b128 v[28:31], v36 offset:2048
	v_fmac_f32_e32 v32, v14, v34
	v_add_f32_e32 v32, v33, v32
	v_add_f32_e32 v37, v37, v32
	ds_read_b128 v[32:35], v36 offset:2064
	s_waitcnt lgkmcnt(1)
	v_mul_f32_e32 v29, v21, v29
	v_fmac_f32_e32 v29, v20, v28
	v_mul_f32_e32 v28, v23, v31
	v_fmac_f32_e32 v28, v22, v30
	v_add_f32_e32 v28, v29, v28
	s_waitcnt lgkmcnt(0)
	v_mul_f32_e32 v29, v25, v33
	v_mul_f32_e32 v30, v27, v35
	v_fmac_f32_e32 v29, v24, v32
	v_fmac_f32_e32 v30, v26, v34
	v_add_f32_e32 v28, v37, v28
	v_add_f32_e32 v29, v29, v30
	v_add_f32_e32 v28, v28, v29
	v_mov_b32_e32 v29, v2
	s_nop 0
	v_add_f32_dpp v28, v28, v28 quad_perm:[1,0,3,2] row_mask:0xf bank_mask:0xf bound_ctrl:1
	s_nop 1
	v_add_f32_dpp v28, v28, v28 quad_perm:[2,3,0,1] row_mask:0xf bank_mask:0xf bound_ctrl:1
	s_nop 1
	v_add_f32_dpp v28, v28, v28 row_half_mirror row_mask:0xf bank_mask:0xf bound_ctrl:1
	s_nop 1
	v_add_f32_dpp v28, v28, v28 row_mirror row_mask:0xf bank_mask:0xf bound_ctrl:1
	s_nop 1
	v_mov_b32_dpp v29, v28 row_bcast:15 row_mask:0xa bank_mask:0xf
	v_add_f32_e32 v28, v28, v29
	v_mov_b32_e32 v29, v2
	s_nop 1
	v_mov_b32_dpp v29, v28 row_bcast:31 row_mask:0xc bank_mask:0xf
	v_add_f32_e32 v32, v28, v29
	ds_read_b128 v[28:31], v40
	v_readlane_b32 s28, v32, 63
	ds_read_b128 v[32:35], v40 offset:2064
	ds_read_b128 v[36:39], v40 offset:2048
	ds_read_b128 v[40:43], v40 offset:16
	s_waitcnt lgkmcnt(3)
	v_mul_f32_e32 v29, v17, v29
	v_fmac_f32_e32 v29, v16, v28
	v_mul_f32_e32 v28, v19, v31
	v_fmac_f32_e32 v28, v18, v30
	v_add_f32_e32 v28, v29, v28
	s_waitcnt lgkmcnt(0)
	v_mul_f32_e32 v29, v13, v41
	v_mul_f32_e32 v30, v15, v43
	v_fmac_f32_e32 v29, v12, v40
	v_fmac_f32_e32 v30, v14, v42
	v_add_f32_e32 v28, 0, v28
	v_add_f32_e32 v29, v29, v30
	v_add_f32_e32 v28, v29, v28
	v_mul_f32_e32 v29, v21, v37
	v_mul_f32_e32 v30, v23, v39
	v_fmac_f32_e32 v29, v20, v36
	v_fmac_f32_e32 v30, v22, v38
	v_add_f32_e32 v29, v29, v30
	v_add_f32_e32 v28, v29, v28
	v_mul_f32_e32 v29, v25, v33
	v_mul_f32_e32 v30, v27, v35
	v_fmac_f32_e32 v29, v24, v32
	v_fmac_f32_e32 v30, v26, v34
	v_add_f32_e32 v29, v29, v30
	v_add_f32_e32 v28, v29, v28
	v_mov_b32_e32 v29, v2
	v_add_u32_e32 v36, 0x15000, v44
	v_add_f32_dpp v28, v28, v28 quad_perm:[1,0,3,2] row_mask:0xf bank_mask:0xf bound_ctrl:1
	v_mov_b32_e32 v33, v2
	v_add_u32_e32 v40, 0x18000, v44
	v_add_f32_dpp v28, v28, v28 quad_perm:[2,3,0,1] row_mask:0xf bank_mask:0xf bound_ctrl:1
	s_nop 1
	v_add_f32_dpp v28, v28, v28 row_half_mirror row_mask:0xf bank_mask:0xf bound_ctrl:1
	s_nop 1
	v_add_f32_dpp v28, v28, v28 row_mirror row_mask:0xf bank_mask:0xf bound_ctrl:1
	s_nop 1
	v_mov_b32_dpp v29, v28 row_bcast:15 row_mask:0xa bank_mask:0xf
	v_add_f32_e32 v32, v28, v29
	ds_read_b128 v[28:31], v36
	s_nop 0
	v_mov_b32_dpp v33, v32 row_bcast:31 row_mask:0xc bank_mask:0xf
	v_add_f32_e32 v32, v32, v33
	s_nop 0
	v_readlane_b32 s29, v32, 63
	ds_read_b128 v[32:35], v36 offset:16
	s_waitcnt lgkmcnt(1)
; #define LAS __attribute__((address_space(3)))
; __device__ __forceinline__ float wave_sum(float v) { return rdlane(dpp_sum63(v), 63); }
; __device__ __forceinline__ void row_finalize(CArgs& A, Frame& F, int m, const f32x4 (&v)[4], int Ln) {
;     ...
;     for (int c = 0; c < 8; ++c) { float s = 0.f;
; #pragma unroll
;         for (int j = 0; j < 4; ++j) { const f32x4 w = *(const LAS f32x4*)(wig + c * 1024 + RCOL(F.lane, j)); s += (v[j][0] * w[0] + v[j][1] * w[1]) + (v[j][2] * w[2] + v[j][3] * w[3]); }
;         r[c] = wave_sum(s); if (c & 1) asm volatile("" ::: "memory"); }
	v_mul_f32_e32 v29, v17, v29
	v_fmac_f32_e32 v29, v16, v28
	v_mul_f32_e32 v28, v19, v31
	v_fmac_f32_e32 v28, v18, v30
	v_add_f32_e32 v28, v29, v28
	s_waitcnt lgkmcnt(0)
	v_mul_f32_e32 v33, v13, v33
	v_add_f32_e32 v37, 0, v28
	v_fmac_f32_e32 v33, v12, v32
	v_mul_f32_e32 v32, v15, v35
	ds_read_b128 v[28:31], v36 offset:2048
	v_fmac_f32_e32 v32, v14, v34
	v_add_f32_e32 v32, v33, v32
	v_add_f32_e32 v37, v37, v32
	ds_read_b128 v[32:35], v36 offset:2064
	s_waitcnt lgkmcnt(1)
	v_mul_f32_e32 v29, v21, v29
	v_fmac_f32_e32 v29, v20, v28
	v_mul_f32_e32 v28, v23, v31
	v_fmac_f32_e32 v28, v22, v30
	v_add_f32_e32 v28, v29, v28
	s_waitcnt lgkmcnt(0)
	v_mul_f32_e32 v29, v25, v33
	v_mul_f32_e32 v30, v27, v35
	v_fmac_f32_e32 v29, v24, v32
	v_fmac_f32_e32 v30, v26, v34
	v_add_f32_e32 v28, v37, v28
	v_add_f32_e32 v29, v29, v30
	v_add_f32_e32 v28, v28, v29
	v_mov_b32_e32 v29, v2
	v_add_u32_e32 v36, 0x16000, v44
	v_add_f32_dpp v28, v28, v28 quad_perm:[1,0,3,2] row_mask:0xf bank_mask:0xf bound_ctrl:1
	v_mov_b32_e32 v33, v2
	s_nop 0
	v_add_f32_dpp v28, v28, v28 quad_perm:[2,3,0,1] row_mask:0xf bank_mask:0xf bound_ctrl:1
	s_nop 1
	v_add_f32_dpp v28, v28, v28 row_half_mirror row_mask:0xf bank_mask:0xf bound_ctrl:1
	s_nop 1
	v_add_f32_dpp v28, v28, v28 row_mirror row_mask:0xf bank_mask:0xf bound_ctrl:1
	s_nop 1
	v_mov_b32_dpp v29, v28 row_bcast:15 row_mask:0xa bank_mask:0xf
	v_add_f32_e32 v32, v28, v29
	ds_read_b128 v[28:31], v36
	s_nop 0
	v_mov_b32_dpp v33, v32 row_bcast:31 row_mask:0xc bank_mask:0xf
	v_add_f32_e32 v32, v32, v33
	s_nop 0
	v_readlane_b32 s36, v32, 63
	ds_read_b128 v[32:35], v36 offset:16
	s_waitcnt lgkmcnt(1)
	v_mul_f32_e32 v29, v17, v29
	v_fmac_f32_e32 v29, v16, v28
	v_mul_f32_e32 v28, v19, v31
	v_fmac_f32_e32 v28, v18, v30
	v_add_f32_e32 v28, v29, v28
	s_waitcnt lgkmcnt(0)
	v_mul_f32_e32 v33, v13, v33
	v_add_f32_e32 v37, 0, v28
	v_fmac_f32_e32 v33, v12, v32
	v_mul_f32_e32 v32, v15, v35
	ds_read_b128 v[28:31], v36 offset:2048
	v_fmac_f32_e32 v32, v14, v34
	v_add_f32_e32 v32, v33, v32
	v_add_f32_e32 v37, v37, v32
	ds_read_b128 v[32:35], v36 offset:2064
	s_waitcnt lgkmcnt(1)
	v_mul_f32_e32 v29, v21, v29
	v_fmac_f32_e32 v29, v20, v28
	v_mul_f32_e32 v28, v23, v31
	v_fmac_f32_e32 v28, v22, v30
	v_add_f32_e32 v28, v29, v28
	s_waitcnt lgkmcnt(0)
	v_mul_f32_e32 v29, v25, v33
	v_mul_f32_e32 v30, v27, v35
	v_fmac_f32_e32 v29, v24, v32
	v_fmac_f32_e32 v30, v26, v34
	v_add_f32_e32 v28, v37, v28
	v_add_f32_e32 v29, v29, v30
	v_add_f32_e32 v28, v28, v29
	v_mov_b32_e32 v29, v2
	v_add_u32_e32 v36, 0x17000, v44
	v_add_f32_dpp v28, v28, v28 quad_perm:[1,0,3,2] row_mask:0xf bank_mask:0xf bound_ctrl:1
	v_mov_b32_e32 v33, v2
	s_nop 0
	v_add_f32_dpp v28, v28, v28 quad_perm:[2,3,0,1] row_mask:0xf bank_mask:0xf bound_ctrl:1
	s_nop 1
	v_add_f32_dpp v28, v28, v28 row_half_mirror row_mask:0xf bank_mask:0xf bound_ctrl:1
	s_nop 1
	v_add_f32_dpp v28, v28, v28 row_mirror row_mask:0xf bank_mask:0xf bound_ctrl:1
	s_nop 1
	v_mov_b32_dpp v29, v28 row_bcast:15 row_mask:0xa bank_mask:0xf
	v_add_f32_e32 v32, v28, v29
	ds_read_b128 v[28:31], v36
	s_nop 0
	v_mov_b32_dpp v33, v32 row_bcast:31 row_mask:0xc bank_mask:0xf
	v_add_f32_e32 v32, v32, v33
	s_nop 0
	v_readlane_b32 s37, v32, 63
	ds_read_b128 v[32:35], v36 offset:16
	s_waitcnt lgkmcnt(1)
	v_mul_f32_e32 v29, v17, v29
	v_fmac_f32_e32 v29, v16, v28
	v_mul_f32_e32 v28, v19, v31
	v_fmac_f32_e32 v28, v18, v30
	v_add_f32_e32 v28, v29, v28
	s_waitcnt lgkmcnt(0)
	v_mul_f32_e32 v33, v13, v33
	v_add_f32_e32 v37, 0, v28
	v_fmac_f32_e32 v33, v12, v32
	v_mul_f32_e32 v32, v15, v35
	ds_read_b128 v[28:31], v36 offset:2048
	v_fmac_f32_e32 v32, v14, v34
	v_add_f32_e32 v32, v33, v32
	v_add_f32_e32 v37, v37, v32
	ds_read_b128 v[32:35], v36 offset:2064
	s_waitcnt lgkmcnt(1)
	v_mul_f32_e32 v29, v21, v29
	v_fmac_f32_e32 v29, v20, v28
	v_mul_f32_e32 v28, v23, v31
	v_fmac_f32_e32 v28, v22, v30
	v_add_f32_e32 v28, v29, v28
	s_waitcnt lgkmcnt(0)
	v_mul_f32_e32 v29, v25, v33
	v_mul_f32_e32 v30, v27, v35
	v_fmac_f32_e32 v29, v24, v32
	v_fmac_f32_e32 v30, v26, v34
	v_add_f32_e32 v28, v37, v28
	v_add_f32_e32 v29, v29, v30
	v_add_f32_e32 v28, v28, v29
	v_mov_b32_e32 v29, v2
	s_nop 0
	v_add_f32_dpp v28, v28, v28 quad_perm:[1,0,3,2] row_mask:0xf bank_mask:0xf bound_ctrl:1
	s_nop 1
	v_add_f32_dpp v28, v28, v28 quad_perm:[2,3,0,1] row_mask:0xf bank_mask:0xf bound_ctrl:1
	s_nop 1
	v_add_f32_dpp v28, v28, v28 row_half_mirror row_mask:0xf bank_mask:0xf bound_ctrl:1
	s_nop 1
	v_add_f32_dpp v28, v28, v28 row_mirror row_mask:0xf bank_mask:0xf bound_ctrl:1
	s_nop 1
	v_mov_b32_dpp v29, v28 row_bcast:15 row_mask:0xa bank_mask:0xf
	v_add_f32_e32 v28, v28, v29
	v_mov_b32_e32 v29, v2
	s_nop 1
	v_mov_b32_dpp v29, v28 row_bcast:31 row_mask:0xc bank_mask:0xf
	v_add_f32_e32 v32, v28, v29
	ds_read_b128 v[28:31], v40
	v_readlane_b32 s56, v32, 63
	ds_read_b128 v[32:35], v40 offset:2064
	ds_read_b128 v[36:39], v40 offset:2048
	ds_read_b128 v[40:43], v40 offset:16
	s_waitcnt lgkmcnt(3)
; #define LAS __attribute__((address_space(3)))
; __device__ __forceinline__ float wave_sum(float v) { return rdlane(dpp_sum63(v), 63); }
; __device__ __forceinline__ void row_finalize(CArgs& A, Frame& F, int m, const f32x4 (&v)[4], int Ln) {
;     ...
;     for (int c = 0; c < 8; ++c) { float s = 0.f;
; #pragma unroll
;         for (int j = 0; j < 4; ++j) { const f32x4 w = *(const LAS f32x4*)(wig + c * 1024 + RCOL(F.lane, j)); s += (v[j][0] * w[0] + v[j][1] * w[1]) + (v[j][2] * w[2] + v[j][3] * w[3]); }
;         r[c] = wave_sum(s); if (c & 1) asm volatile("" ::: "memory"); }
;     if (F.lane < 8) { float x = r[0];
; #pragma unroll
;         for (int c = 1; c < 8; ++c) x = (F.lane == c) ? r[c] : x;
;         WSP(float, WS_IGFG)[(size_t)m * 8 + F.lane] = x + b_in[F.lane]; }
	v_mul_f32_e32 v29, v17, v29
	v_fmac_f32_e32 v29, v16, v28
	v_mul_f32_e32 v28, v19, v31
	v_fmac_f32_e32 v28, v18, v30
	v_add_f32_e32 v28, v29, v28
	s_waitcnt lgkmcnt(0)
	v_mul_f32_e32 v29, v13, v41
	v_mul_f32_e32 v30, v15, v43
	v_fmac_f32_e32 v29, v12, v40
	v_fmac_f32_e32 v30, v14, v42
	v_add_f32_e32 v28, 0, v28
	v_add_f32_e32 v29, v29, v30
	v_add_f32_e32 v28, v29, v28
	v_mul_f32_e32 v29, v21, v37
	v_mul_f32_e32 v30, v23, v39
	v_fmac_f32_e32 v29, v20, v36
	v_fmac_f32_e32 v30, v22, v38
	v_add_f32_e32 v29, v29, v30
	v_add_f32_e32 v28, v29, v28
	v_mul_f32_e32 v29, v25, v33
	v_mul_f32_e32 v30, v27, v35
	v_fmac_f32_e32 v29, v24, v32
	v_fmac_f32_e32 v30, v26, v34
	v_add_f32_e32 v29, v29, v30
	v_add_f32_e32 v28, v29, v28
	v_mov_b32_e32 v29, v2
	v_mov_b32_e32 v33, v2
	v_add_f32_dpp v28, v28, v28 quad_perm:[1,0,3,2] row_mask:0xf bank_mask:0xf bound_ctrl:1
	v_add_u32_e32 v36, 0x19000, v44
	s_nop 0
	v_add_f32_dpp v28, v28, v28 quad_perm:[2,3,0,1] row_mask:0xf bank_mask:0xf bound_ctrl:1
	s_nop 1
	v_add_f32_dpp v28, v28, v28 row_half_mirror row_mask:0xf bank_mask:0xf bound_ctrl:1
	s_nop 1
	v_add_f32_dpp v28, v28, v28 row_mirror row_mask:0xf bank_mask:0xf bound_ctrl:1
	s_nop 1
	v_mov_b32_dpp v29, v28 row_bcast:15 row_mask:0xa bank_mask:0xf
	v_add_f32_e32 v32, v28, v29
	ds_read_b128 v[28:31], v36
	s_nop 0
	v_mov_b32_dpp v33, v32 row_bcast:31 row_mask:0xc bank_mask:0xf
	v_add_f32_e32 v32, v32, v33
	s_nop 0
	v_readlane_b32 s57, v32, 63
	ds_read_b128 v[32:35], v36 offset:16
	s_waitcnt lgkmcnt(1)
	v_mul_f32_e32 v17, v17, v29
	v_fmac_f32_e32 v17, v16, v28
	v_mul_f32_e32 v16, v19, v31
	v_fmac_f32_e32 v16, v18, v30
	s_waitcnt lgkmcnt(0)
	v_mul_f32_e32 v13, v13, v33
	v_fmac_f32_e32 v13, v12, v32
	v_mul_f32_e32 v12, v15, v35
	v_add_f32_e32 v16, v17, v16
	v_fmac_f32_e32 v12, v14, v34
	v_add_f32_e32 v28, 0, v16
	ds_read_b128 v[16:19], v36 offset:2048
	v_add_f32_e32 v12, v13, v12
	v_add_f32_e32 v28, v28, v12
	ds_read_b128 v[12:15], v36 offset:2064
	s_waitcnt lgkmcnt(1)
	v_mul_f32_e32 v17, v21, v17
	v_fmac_f32_e32 v17, v20, v16
	v_mul_f32_e32 v16, v23, v19
	s_waitcnt lgkmcnt(0)
	v_mul_f32_e32 v13, v25, v13
	v_fmac_f32_e32 v16, v22, v18
	v_fmac_f32_e32 v13, v24, v12
	v_mul_f32_e32 v12, v27, v15
	v_add_f32_e32 v16, v17, v16
	v_fmac_f32_e32 v12, v26, v14
	v_add_f32_e32 v16, v28, v16
	v_add_f32_e32 v12, v13, v12
	v_add_f32_e32 v12, v16, v12
	v_mov_b32_e32 v13, v2
	s_nop 0
	v_add_f32_dpp v12, v12, v12 quad_perm:[1,0,3,2] row_mask:0xf bank_mask:0xf bound_ctrl:1
	s_nop 1
	v_add_f32_dpp v12, v12, v12 quad_perm:[2,3,0,1] row_mask:0xf bank_mask:0xf bound_ctrl:1
	s_nop 1
	v_add_f32_dpp v12, v12, v12 row_half_mirror row_mask:0xf bank_mask:0xf bound_ctrl:1
	s_nop 1
	v_add_f32_dpp v12, v12, v12 row_mirror row_mask:0xf bank_mask:0xf bound_ctrl:1
	s_nop 1
	v_mov_b32_dpp v13, v12 row_bcast:15 row_mask:0xa bank_mask:0xf
	v_add_f32_e32 v12, v12, v13
	v_mov_b32_e32 v13, v2
	s_nop 1
	v_mov_b32_dpp v13, v12 row_bcast:31 row_mask:0xc bank_mask:0xf
	v_add_f32_e32 v12, v12, v13
	s_nop 0
	v_readlane_b32 s60, v12, 63
	s_and_saveexec_b64 s[10:11], s[38:39]
	s_cbranch_execz .LBB0_1716
	s_load_dwordx2 s[64:65], s[2:3], 0x50
	v_mov_b32_e32 v12, s27
	v_mov_b32_e32 v13, s28
	v_cndmask_b32_e64 v12, v12, v13, s[40:41]
	v_mov_b32_e32 v13, s29
	v_cndmask_b32_e64 v12, v12, v13, s[42:43]
	v_mov_b32_e32 v13, s36
	v_cndmask_b32_e64 v12, v12, v13, s[44:45]
	v_mov_b32_e32 v13, s37
	v_cndmask_b32_e64 v12, v12, v13, s[46:47]
	v_mov_b32_e32 v13, s56
	s_waitcnt lgkmcnt(0)
	s_add_u32 s64, s64, s26
	v_cndmask_b32_e64 v12, v12, v13, s[48:49]
	v_mov_b32_e32 v13, s57
	s_addc_u32 s65, s65, s13
	v_cndmask_b32_e64 v12, v12, v13, s[50:51]
	v_mov_b32_e32 v13, s60
	v_cndmask_b32_e64 v14, v12, v13, s[52:53]
	v_lshl_add_u64 v[12:13], v[0:1], 2, s[64:65]
	v_add_co_u32_e32 v12, vcc, 0x3000, v12
	s_nop 1
	v_addc_co_u32_e32 v13, vcc, 0, v13, vcc
	v_mov_b32_e32 v12, v168
	s_nop 0
	v_add_f32_e32 v14, v14, v12
	v_lshl_add_u64 v[12:13], s[58:59], 0, v[68:69]
	global_store_dword v[12:13], v14, off

; __device__ __forceinline__ float bflo(unsigned w) { return __uint_as_float(w << 16); }
; __device__ __forceinline__ float bfhi(unsigned w) { return __uint_as_float(w & 0xffff0000u); }
; __device__ __forceinline__ float wave_sum(float v) { return rdlane(dpp_sum63(v), 63); }
; __device__ __forceinline__ void row_unpack(const u32x4 (&r)[2], f32x4 (&v)[4]) {
; #pragma unroll
;     for (int j = 0; j < 2; ++j) { v[2 * j] = (f32x4){bflo(r[j].x), bfhi(r[j].x), bflo(r[j].y), bfhi(r[j].y)}; v[2 * j + 1] = (f32x4){bflo(r[j].z), bfhi(r[j].z), bflo(r[j].w), bfhi(r[j].w)}; }
; }
; __device__ __forceinline__ void row_ln(f32x4 (&v)[4], const float* g, const float* b, int lane) {
;     float s = 0.f;
; #pragma unroll
;     for (int j = 0; j < 4; ++j) s += (v[j][0] + v[j][1]) + (v[j][2] + v[j][3]);
;     const float mean = wave_sum(s) * (1.f / D); float s2 = 0.f;
; #pragma unroll
;     for (int j = 0; j < 4; ++j) { v[j] = v[j] - mean; s2 += (v[j][0] * v[j][0] + v[j][1] * v[j][1]) + (v[j][2] * v[j][2] + v[j][3] * v[j][3]); }
;     const float rstd = 1.0f / sqrtf(wave_sum(s2) * (1.f / D) + LN_EPS);
; #pragma unroll
;     for (int j = 0; j < 4; ++j) { const f32x4 gg = *(const f32x4*)(g + RCOL(lane, j)), bb = *(const f32x4*)(b + RCOL(lane, j)); v[j] = v[j] * rstd * gg + bb; }
.LBB0_1717:
	s_cmp_ge_i32 s7, s8
	s_cbranch_scc1 .LBB0_1696
	v_lshlrev_b32_e32 v38, 16, v8
	v_and_b32_e32 v39, 0xffff0000, v8
	v_lshlrev_b32_e32 v36, 16, v9
	v_and_b32_e32 v37, 0xffff0000, v9
	v_lshlrev_b32_e32 v9, 16, v5
	v_lshlrev_b32_e32 v8, 16, v4
	v_and_b32_e32 v5, 0xffff0000, v5
	v_and_b32_e32 v4, 0xffff0000, v4
	v_lshlrev_b32_e32 v30, 16, v10
	v_and_b32_e32 v34, 0xffff0000, v10
	v_lshlrev_b32_e32 v28, 16, v11
	v_and_b32_e32 v32, 0xffff0000, v11
	v_pk_add_f32 v[10:11], v[8:9], v[4:5]
	v_lshlrev_b32_e32 v13, 16, v7
	v_add_f32_e32 v10, v10, v11
	v_lshlrev_b32_e32 v12, 16, v6
	v_and_b32_e32 v7, 0xffff0000, v7
	v_and_b32_e32 v6, 0xffff0000, v6
	v_add_f32_e32 v33, 0, v10
	v_pk_add_f32 v[10:11], v[12:13], v[6:7]
	v_add_f32_e32 v31, v38, v39
	v_pk_add_f32 v[10:11], v[10:11], v[10:11] op_sel_hi:[0,1]
	v_add_f32_e32 v35, v36, v37
	v_mov_b32_e32 v29, v11
	v_pk_add_f32 v[14:15], v[30:31], v[34:35]
	v_pk_add_f32 v[10:11], v[28:29], v[32:33]
	s_nop 0
	v_pk_add_f32 v[10:11], v[14:15], v[10:11]
	s_nop 0
	v_add_f32_e32 v10, v10, v11
	v_mov_b32_e32 v11, v2
	s_nop 0
	v_add_f32_dpp v10, v10, v10 quad_perm:[1,0,3,2] row_mask:0xf bank_mask:0xf bound_ctrl:1
	s_nop 1
	v_add_f32_dpp v10, v10, v10 quad_perm:[2,3,0,1] row_mask:0xf bank_mask:0xf bound_ctrl:1
	s_nop 1
	v_add_f32_dpp v10, v10, v10 row_half_mirror row_mask:0xf bank_mask:0xf bound_ctrl:1
	s_nop 1
	v_add_f32_dpp v10, v10, v10 row_mirror row_mask:0xf bank_mask:0xf bound_ctrl:1
	s_nop 1
	v_mov_b32_dpp v11, v10 row_bcast:15 row_mask:0xa bank_mask:0xf
	v_add_f32_e32 v10, v10, v11
	v_mov_b32_e32 v11, v2
	s_nop 1
	v_mov_b32_dpp v11, v10 row_bcast:31 row_mask:0xc bank_mask:0xf
	v_add_f32_e32 v10, v10, v11
	s_nop 0
	v_readlane_b32 s7, v10, 63
	s_nop 1
	v_fmac_f32_e32 v5, s7, v236
	v_fmac_f32_e32 v4, s7, v236
	v_fmac_f32_e32 v9, s7, v236
	v_fmac_f32_e32 v8, s7, v236
	v_mul_f32_e32 v10, v4, v4
	v_mul_f32_e32 v11, v5, v5
	v_fmac_f32_e32 v10, v8, v8
	v_fmac_f32_e32 v11, v9, v9
	v_fmac_f32_e32 v7, s7, v236
	v_fmac_f32_e32 v6, s7, v236
	v_add_f32_e32 v10, v10, v11
	v_fmac_f32_e32 v13, s7, v236
	v_fmac_f32_e32 v12, s7, v236
	v_mul_f32_e32 v11, v6, v6
	v_mul_f32_e32 v14, v7, v7
	v_fmac_f32_e32 v11, v12, v12
	v_fmac_f32_e32 v14, v13, v13
	v_add_f32_e32 v11, v11, v14
	v_fmac_f32_e32 v37, s7, v236
	v_fmac_f32_e32 v39, s7, v236
	v_add_f32_e32 v10, v10, v11
	v_fmac_f32_e32 v36, s7, v236
	v_fmac_f32_e32 v38, s7, v236
	v_mul_f32_e32 v11, v39, v39
	v_mul_f32_e32 v14, v37, v37
	v_fmac_f32_e32 v11, v38, v38
	v_fmac_f32_e32 v14, v36, v36
	v_add_f32_e32 v11, v11, v14
	v_fmac_f32_e32 v32, s7, v236
	v_fmac_f32_e32 v34, s7, v236
	v_add_f32_e32 v10, v11, v10
	v_fmac_f32_e32 v28, s7, v236
	v_fmac_f32_e32 v30, s7, v236
	v_mul_f32_e32 v11, v34, v34
	v_mul_f32_e32 v14, v32, v32
	v_fmac_f32_e32 v11, v30, v30
	v_fmac_f32_e32 v14, v28, v28
	v_add_f32_e32 v11, v11, v14
	v_add_f32_e32 v10, v11, v10
	v_mov_b32_e32 v11, v2
	v_mov_b32_e32 v31, v34
	v_add_f32_dpp v10, v10, v10 quad_perm:[1,0,3,2] row_mask:0xf bank_mask:0xf bound_ctrl:1
	v_mov_b32_e32 v29, v32
	s_nop 0
	v_add_f32_dpp v10, v10, v10 quad_perm:[2,3,0,1] row_mask:0xf bank_mask:0xf bound_ctrl:1
	s_nop 1
	v_add_f32_dpp v10, v10, v10 row_half_mirror row_mask:0xf bank_mask:0xf bound_ctrl:1
	s_nop 1
	v_add_f32_dpp v10, v10, v10 row_mirror row_mask:0xf bank_mask:0xf bound_ctrl:1
	s_nop 1
	v_mov_b32_dpp v11, v10 row_bcast:15 row_mask:0xa bank_mask:0xf
	v_add_f32_e32 v10, v10, v11
	v_mov_b32_e32 v11, v2
	s_nop 1
	v_mov_b32_dpp v11, v10 row_bcast:31 row_mask:0xc bank_mask:0xf
	v_add_f32_e32 v10, v10, v11
	s_nop 0
	v_readlane_b32 s7, v10, 63
	s_nop 1
	v_fma_f32 v10, s7, v237, v252
	v_cmp_gt_f32_e32 vcc, s31, v10
	v_mul_f32_e32 v11, 0x4f800000, v10
	s_nop 0
	v_cndmask_b32_e32 v10, v10, v11, vcc
	v_sqrt_f32_e32 v11, v10
	s_nop 0
	v_add_u32_e32 v14, -1, v11
	v_fma_f32 v15, -v14, v11, v10
	v_cmp_ge_f32_e64 s[56:57], 0, v15
	v_add_u32_e32 v15, 1, v11
	s_nop 0
	v_cndmask_b32_e64 v14, v11, v14, s[56:57]
	v_fma_f32 v11, -v15, v11, v10
	v_cmp_lt_f32_e64 s[56:57], 0, v11
	s_nop 1
	v_cndmask_b32_e64 v11, v14, v15, s[56:57]
	v_mul_f32_e32 v14, 0x37800000, v11
	v_cndmask_b32_e32 v11, v11, v14, vcc
	v_cmp_class_f32_e32 vcc, v10, v234
	s_nop 1
	v_cndmask_b32_e32 v10, v11, v10, vcc
	v_div_scale_f32 v11, s[10:11], v10, v10, 1.0
	v_rcp_f32_e32 v14, v11
	s_mov_b64 s[10:11], -1
	v_fma_f32 v15, -v11, v14, 1.0
	v_fmac_f32_e32 v14, v15, v14
	v_div_scale_f32 v15, vcc, 1.0, v10, 1.0
	v_mul_f32_e32 v16, v15, v14
	v_fma_f32 v17, -v11, v16, v15
	v_fmac_f32_e32 v16, v17, v14
	v_fma_f32 v11, -v11, v16, v15
	v_div_fmas_f32 v11, v11, v14, v16
	v_mov_b64_e32 v[14:15], v[108:109]
	v_mov_b64_e32 v[16:17], v[110:111]
	v_mov_b64_e32 v[18:19], v[104:105]
	v_mov_b64_e32 v[20:21], v[106:107]
	v_mov_b64_e32 v[22:23], v[124:125]
	v_mov_b64_e32 v[24:25], v[126:127]
	v_mov_b64_e32 v[42:43], v[120:121]
	v_mov_b64_e32 v[44:45], v[122:123]
	v_div_fixup_f32 v40, v11, v10, 1.0
	v_mov_b32_e32 v11, v4
	v_mov_b32_e32 v4, v9
	v_mov_b32_e32 v10, v8
	v_pk_mul_f32 v[4:5], v[4:5], v[40:41] op_sel_hi:[1,0]
	v_pk_mul_f32 v[26:27], v[10:11], v[40:41] op_sel_hi:[1,0]
	v_pk_mul_f32 v[38:39], v[38:39], v[40:41] op_sel_hi:[1,0]
	v_pk_mul_f32 v[36:37], v[36:37], v[40:41] op_sel_hi:[1,0]
	s_and_b64 vcc, exec, s[54:55]
	s_nop 0
	v_pk_fma_f32 v[10:11], v[20:21], v[4:5], v[44:45]
	v_mov_b32_e32 v4, v12
	v_mov_b32_e32 v5, v6
	v_mov_b32_e32 v6, v13
	v_pk_mul_f32 v[4:5], v[4:5], v[40:41] op_sel_hi:[1,0]
	v_pk_mul_f32 v[6:7], v[6:7], v[40:41] op_sel_hi:[1,0]
	v_pk_fma_f32 v[8:9], v[18:19], v[26:27], v[42:43]
	v_pk_fma_f32 v[6:7], v[16:17], v[6:7], v[24:25]
	v_pk_fma_f32 v[4:5], v[14:15], v[4:5], v[22:23]
	v_mov_b64_e32 v[16:17], v[116:117]
	v_mov_b64_e32 v[18:19], v[118:119]
	v_mov_b64_e32 v[12:13], v[112:113]
	v_mov_b64_e32 v[14:15], v[114:115]
	v_mov_b64_e32 v[20:21], v[132:133]
	v_mov_b64_e32 v[22:23], v[134:135]
	v_mov_b64_e32 v[24:25], v[128:129]
	v_mov_b64_e32 v[26:27], v[130:131]
	s_nop 0
	v_pk_fma_f32 v[14:15], v[14:15], v[36:37], v[26:27]
	v_pk_fma_f32 v[12:13], v[12:13], v[38:39], v[24:25]
	v_pk_mul_f32 v[24:25], v[30:31], v[40:41] op_sel_hi:[1,0]
	v_pk_mul_f32 v[26:27], v[28:29], v[40:41] op_sel_hi:[1,0]
	v_pk_fma_f32 v[16:17], v[16:17], v[24:25], v[20:21]
	v_pk_fma_f32 v[18:19], v[18:19], v[26:27], v[22:23]
	s_cbranch_vccnz .LBB0_1720
	v_lshl_add_u64 v[20:21], s[18:19], 0, v[54:55]
	s_mov_b64 s[10:11], 0
	global_store_dwordx4 v[20:21], v[8:11], off
	global_store_dwordx4 v[20:21], v[4:7], off offset:16
	global_store_dwordx4 v[20:21], v[12:15], off offset:2048
	global_store_dwordx4 v[20:21], v[16:19], off offset:2064
; #define LAS __attribute__((address_space(3)))
; __device__ __forceinline__ float wave_sum(float v) { return rdlane(dpp_sum63(v), 63); }
; __device__ __forceinline__ void row_finalize(CArgs& A, Frame& F, int m, const f32x4 (&v)[4], int Ln) {
;     row_store_bf(WSP(bf16, WS_X) + (size_t)m * D, F.lane, v);
;     const LAS float* wig = (const LAS float*)(F.lds + WIG_OFF); const float* b_in = A.in[10] + (size_t)Ln * DIN + 3072;
;     float r[8];
; #pragma unroll
;     for (int c = 0; c < 8; ++c) { float s = 0.f;
; #pragma unroll
;         for (int j = 0; j < 4; ++j) { const f32x4 w = *(const LAS f32x4*)(wig + c * 1024 + RCOL(F.lane, j)); s += (v[j][0] * w[0] + v[j][1] * w[1]) + (v[j][2] * w[2] + v[j][3] * w[3]); }
;         r[c] = wave_sum(s); if (c & 1) asm volatile("" ::: "memory"); }
.LBB0_1720:
	s_andn2_b64 vcc, exec, s[10:11]
	s_cbranch_vccnz .LBB0_1696
	v_lshl_add_u64 v[24:25], s[58:59], 0, v[66:67]
	s_mov_b32 s7, 0x7680000
	v_add_co_u32_e32 v28, vcc, s7, v24
	v_add_u32_e32 v36, 0, v3
	v_cvt_pk_bf16_f32 v20, v8, v9
	v_cvt_pk_bf16_f32 v21, v10, v11
	v_cvt_pk_bf16_f32 v22, v4, v5
	v_cvt_pk_bf16_f32 v23, v6, v7
	s_nop 0
	v_addc_co_u32_e32 v29, vcc, 0, v25, vcc
	v_add_u32_e32 v30, 0x12000, v36
	global_store_dwordx4 v[28:29], v[20:23], off
	v_add_u32_e32 v32, 0x14000, v36
	s_nop 0
	v_cvt_pk_bf16_f32 v20, v12, v13
	v_cvt_pk_bf16_f32 v21, v14, v15
	v_cvt_pk_bf16_f32 v22, v16, v17
	v_cvt_pk_bf16_f32 v23, v18, v19
	ds_read_b128 v[24:27], v30
	global_store_dwordx4 v[28:29], v[20:23], off offset:1024
	ds_read_b128 v[20:23], v30 offset:16
	s_waitcnt lgkmcnt(1)
	v_mul_f32_e32 v25, v9, v25
	v_fmac_f32_e32 v25, v8, v24
	v_mul_f32_e32 v24, v11, v27
	s_waitcnt lgkmcnt(0)
	v_mul_f32_e32 v21, v5, v21
	v_fmac_f32_e32 v24, v10, v26
	v_fmac_f32_e32 v21, v4, v20
	v_mul_f32_e32 v20, v7, v23
	v_add_f32_e32 v24, v25, v24
	v_fmac_f32_e32 v20, v6, v22
	v_add_f32_e32 v28, 0, v24
	ds_read_b128 v[24:27], v30 offset:2048
	v_add_f32_e32 v20, v21, v20
	v_add_f32_e32 v28, v28, v20
	ds_read_b128 v[20:23], v30 offset:2064
	s_waitcnt lgkmcnt(1)
	v_mul_f32_e32 v25, v13, v25
	v_fmac_f32_e32 v25, v12, v24
	v_mul_f32_e32 v24, v15, v27
	s_waitcnt lgkmcnt(0)
	v_mul_f32_e32 v21, v17, v21
	v_fmac_f32_e32 v24, v14, v26
	v_fmac_f32_e32 v21, v16, v20
	v_mul_f32_e32 v20, v19, v23
	v_add_f32_e32 v24, v25, v24
	v_fmac_f32_e32 v20, v18, v22
	v_add_f32_e32 v24, v28, v24
	v_add_f32_e32 v20, v21, v20
	v_add_f32_e32 v20, v24, v20
	v_mov_b32_e32 v21, v2
	v_add_u32_e32 v28, 0x13000, v36
	v_add_f32_dpp v20, v20, v20 quad_perm:[1,0,3,2] row_mask:0xf bank_mask:0xf bound_ctrl:1
	v_mov_b32_e32 v25, v2
	s_nop 0
	v_add_f32_dpp v20, v20, v20 quad_perm:[2,3,0,1] row_mask:0xf bank_mask:0xf bound_ctrl:1
	s_nop 1
	v_add_f32_dpp v20, v20, v20 row_half_mirror row_mask:0xf bank_mask:0xf bound_ctrl:1
	s_nop 1
	v_add_f32_dpp v20, v20, v20 row_mirror row_mask:0xf bank_mask:0xf bound_ctrl:1
	s_nop 1
	v_mov_b32_dpp v21, v20 row_bcast:15 row_mask:0xa bank_mask:0xf
	v_add_f32_e32 v24, v20, v21
	ds_read_b128 v[20:23], v28
	s_nop 0
	v_mov_b32_dpp v25, v24 row_bcast:31 row_mask:0xc bank_mask:0xf
	v_add_f32_e32 v24, v24, v25
	s_nop 0
	v_readlane_b32 s7, v24, 63
	ds_read_b128 v[24:27], v28 offset:16
	s_waitcnt lgkmcnt(1)
	v_mul_f32_e32 v21, v9, v21
	v_fmac_f32_e32 v21, v8, v20
	v_mul_f32_e32 v20, v11, v23
	v_fmac_f32_e32 v20, v10, v22
	v_add_f32_e32 v20, v21, v20
	s_waitcnt lgkmcnt(0)
	v_mul_f32_e32 v25, v5, v25
	v_add_f32_e32 v29, 0, v20
	v_fmac_f32_e32 v25, v4, v24
	v_mul_f32_e32 v24, v7, v27
	ds_read_b128 v[20:23], v28 offset:2048
	v_fmac_f32_e32 v24, v6, v26
	v_add_f32_e32 v24, v25, v24
	v_add_f32_e32 v29, v29, v24
	ds_read_b128 v[24:27], v28 offset:2064
	s_waitcnt lgkmcnt(1)
	v_mul_f32_e32 v21, v13, v21
	v_fmac_f32_e32 v21, v12, v20
	v_mul_f32_e32 v20, v15, v23
	v_fmac_f32_e32 v20, v14, v22
	v_add_f32_e32 v20, v21, v20
	s_waitcnt lgkmcnt(0)
	v_mul_f32_e32 v21, v17, v25
	v_mul_f32_e32 v22, v19, v27
	v_fmac_f32_e32 v21, v16, v24
	v_fmac_f32_e32 v22, v18, v26
	v_add_f32_e32 v20, v29, v20
	v_add_f32_e32 v21, v21, v22
	v_add_f32_e32 v20, v20, v21
	v_mov_b32_e32 v21, v2
	s_nop 0
	v_add_f32_dpp v20, v20, v20 quad_perm:[1,0,3,2] row_mask:0xf bank_mask:0xf bound_ctrl:1
	s_nop 1
	v_add_f32_dpp v20, v20, v20 quad_perm:[2,3,0,1] row_mask:0xf bank_mask:0xf bound_ctrl:1
	s_nop 1
	v_add_f32_dpp v20, v20, v20 row_half_mirror row_mask:0xf bank_mask:0xf bound_ctrl:1
	s_nop 1
	v_add_f32_dpp v20, v20, v20 row_mirror row_mask:0xf bank_mask:0xf bound_ctrl:1
	s_nop 1
	v_mov_b32_dpp v21, v20 row_bcast:15 row_mask:0xa bank_mask:0xf
	v_add_f32_e32 v20, v20, v21
	v_mov_b32_e32 v21, v2
	s_nop 1
	v_mov_b32_dpp v21, v20 row_bcast:31 row_mask:0xc bank_mask:0xf
	v_add_f32_e32 v24, v20, v21
	ds_read_b128 v[20:23], v32
	v_readlane_b32 s27, v24, 63
	ds_read_b128 v[24:27], v32 offset:2064
	ds_read_b128 v[28:31], v32 offset:2048
	ds_read_b128 v[32:35], v32 offset:16
	s_waitcnt lgkmcnt(3)
	v_mul_f32_e32 v21, v9, v21
	v_fmac_f32_e32 v21, v8, v20
	v_mul_f32_e32 v20, v11, v23
	v_fmac_f32_e32 v20, v10, v22
	v_add_f32_e32 v20, v21, v20
	s_waitcnt lgkmcnt(0)
	v_mul_f32_e32 v21, v5, v33
	v_mul_f32_e32 v22, v7, v35
	v_fmac_f32_e32 v21, v4, v32
	v_fmac_f32_e32 v22, v6, v34
	v_add_f32_e32 v20, 0, v20
	v_add_f32_e32 v21, v21, v22
	v_add_f32_e32 v20, v21, v20
	v_mul_f32_e32 v21, v13, v29
	v_mul_f32_e32 v22, v15, v31
	v_fmac_f32_e32 v21, v12, v28
	v_fmac_f32_e32 v22, v14, v30
	v_add_f32_e32 v21, v21, v22
	v_add_f32_e32 v20, v21, v20
	v_mul_f32_e32 v21, v17, v25
	v_mul_f32_e32 v22, v19, v27
	v_fmac_f32_e32 v21, v16, v24
	v_fmac_f32_e32 v22, v18, v26
	v_add_f32_e32 v21, v21, v22
	v_add_f32_e32 v20, v21, v20
	v_mov_b32_e32 v21, v2
	v_add_u32_e32 v28, 0x15000, v36
	v_add_f32_dpp v20, v20, v20 quad_perm:[1,0,3,2] row_mask:0xf bank_mask:0xf bound_ctrl:1
	v_mov_b32_e32 v25, v2
	v_add_u32_e32 v32, 0x18000, v36
	v_add_f32_dpp v20, v20, v20 quad_perm:[2,3,0,1] row_mask:0xf bank_mask:0xf bound_ctrl:1
	s_nop 1
	v_add_f32_dpp v20, v20, v20 row_half_mirror row_mask:0xf bank_mask:0xf bound_ctrl:1
	s_nop 1
	v_add_f32_dpp v20, v20, v20 row_mirror row_mask:0xf bank_mask:0xf bound_ctrl:1
	s_nop 1
	v_mov_b32_dpp v21, v20 row_bcast:15 row_mask:0xa bank_mask:0xf
	v_add_f32_e32 v24, v20, v21
	ds_read_b128 v[20:23], v28
	s_nop 0
	v_mov_b32_dpp v25, v24 row_bcast:31 row_mask:0xc bank_mask:0xf
	v_add_f32_e32 v24, v24, v25
	s_nop 0
	v_readlane_b32 s28, v24, 63
	ds_read_b128 v[24:27], v28 offset:16
	s_waitcnt lgkmcnt(1)
; #define LAS __attribute__((address_space(3)))
; __device__ __forceinline__ float wave_sum(float v) { return rdlane(dpp_sum63(v), 63); }
; __device__ __forceinline__ void row_finalize(CArgs& A, Frame& F, int m, const f32x4 (&v)[4], int Ln) {
;     ...
;     for (int c = 0; c < 8; ++c) { float s = 0.f;
; #pragma unroll
;         for (int j = 0; j < 4; ++j) { const f32x4 w = *(const LAS f32x4*)(wig + c * 1024 + RCOL(F.lane, j)); s += (v[j][0] * w[0] + v[j][1] * w[1]) + (v[j][2] * w[2] + v[j][3] * w[3]); }
;         r[c] = wave_sum(s); if (c & 1) asm volatile("" ::: "memory"); }
	v_mul_f32_e32 v21, v9, v21
	v_fmac_f32_e32 v21, v8, v20
	v_mul_f32_e32 v20, v11, v23
	v_fmac_f32_e32 v20, v10, v22
	v_add_f32_e32 v20, v21, v20
	s_waitcnt lgkmcnt(0)
	v_mul_f32_e32 v25, v5, v25
	v_add_f32_e32 v29, 0, v20
	v_fmac_f32_e32 v25, v4, v24
	v_mul_f32_e32 v24, v7, v27
	ds_read_b128 v[20:23], v28 offset:2048
	v_fmac_f32_e32 v24, v6, v26
	v_add_f32_e32 v24, v25, v24
	v_add_f32_e32 v29, v29, v24
	ds_read_b128 v[24:27], v28 offset:2064
	s_waitcnt lgkmcnt(1)
	v_mul_f32_e32 v21, v13, v21
	v_fmac_f32_e32 v21, v12, v20
	v_mul_f32_e32 v20, v15, v23
	v_fmac_f32_e32 v20, v14, v22
	v_add_f32_e32 v20, v21, v20
	s_waitcnt lgkmcnt(0)
	v_mul_f32_e32 v21, v17, v25
	v_mul_f32_e32 v22, v19, v27
	v_fmac_f32_e32 v21, v16, v24
	v_fmac_f32_e32 v22, v18, v26
	v_add_f32_e32 v20, v29, v20
	v_add_f32_e32 v21, v21, v22
	v_add_f32_e32 v20, v20, v21
	v_mov_b32_e32 v21, v2
	v_add_u32_e32 v28, 0x16000, v36
	v_add_f32_dpp v20, v20, v20 quad_perm:[1,0,3,2] row_mask:0xf bank_mask:0xf bound_ctrl:1
	v_mov_b32_e32 v25, v2
	s_nop 0
	v_add_f32_dpp v20, v20, v20 quad_perm:[2,3,0,1] row_mask:0xf bank_mask:0xf bound_ctrl:1
	s_nop 1
	v_add_f32_dpp v20, v20, v20 row_half_mirror row_mask:0xf bank_mask:0xf bound_ctrl:1
	s_nop 1
	v_add_f32_dpp v20, v20, v20 row_mirror row_mask:0xf bank_mask:0xf bound_ctrl:1
	s_nop 1
	v_mov_b32_dpp v21, v20 row_bcast:15 row_mask:0xa bank_mask:0xf
	v_add_f32_e32 v24, v20, v21
	ds_read_b128 v[20:23], v28
	s_nop 0
	v_mov_b32_dpp v25, v24 row_bcast:31 row_mask:0xc bank_mask:0xf
	v_add_f32_e32 v24, v24, v25
	s_nop 0
	v_readlane_b32 s29, v24, 63
	ds_read_b128 v[24:27], v28 offset:16
	s_waitcnt lgkmcnt(1)
	v_mul_f32_e32 v21, v9, v21
	v_fmac_f32_e32 v21, v8, v20
	v_mul_f32_e32 v20, v11, v23
	v_fmac_f32_e32 v20, v10, v22
	v_add_f32_e32 v20, v21, v20
	s_waitcnt lgkmcnt(0)
	v_mul_f32_e32 v25, v5, v25
	v_add_f32_e32 v29, 0, v20
	v_fmac_f32_e32 v25, v4, v24
	v_mul_f32_e32 v24, v7, v27
	ds_read_b128 v[20:23], v28 offset:2048
	v_fmac_f32_e32 v24, v6, v26
	v_add_f32_e32 v24, v25, v24
	v_add_f32_e32 v29, v29, v24
	ds_read_b128 v[24:27], v28 offset:2064
	s_waitcnt lgkmcnt(1)
	v_mul_f32_e32 v21, v13, v21
	v_fmac_f32_e32 v21, v12, v20
	v_mul_f32_e32 v20, v15, v23
	v_fmac_f32_e32 v20, v14, v22
	v_add_f32_e32 v20, v21, v20
	s_waitcnt lgkmcnt(0)
	v_mul_f32_e32 v21, v17, v25
	v_mul_f32_e32 v22, v19, v27
	v_fmac_f32_e32 v21, v16, v24
	v_fmac_f32_e32 v22, v18, v26
	v_add_f32_e32 v20, v29, v20
	v_add_f32_e32 v21, v21, v22
	v_add_f32_e32 v20, v20, v21
	v_mov_b32_e32 v21, v2
	v_add_u32_e32 v28, 0x17000, v36
	v_add_f32_dpp v20, v20, v20 quad_perm:[1,0,3,2] row_mask:0xf bank_mask:0xf bound_ctrl:1
	v_mov_b32_e32 v25, v2
	s_nop 0
	v_add_f32_dpp v20, v20, v20 quad_perm:[2,3,0,1] row_mask:0xf bank_mask:0xf bound_ctrl:1
	s_nop 1
	v_add_f32_dpp v20, v20, v20 row_half_mirror row_mask:0xf bank_mask:0xf bound_ctrl:1
	s_nop 1
	v_add_f32_dpp v20, v20, v20 row_mirror row_mask:0xf bank_mask:0xf bound_ctrl:1
	s_nop 1
	v_mov_b32_dpp v21, v20 row_bcast:15 row_mask:0xa bank_mask:0xf
	v_add_f32_e32 v24, v20, v21
	ds_read_b128 v[20:23], v28
	s_nop 0
	v_mov_b32_dpp v25, v24 row_bcast:31 row_mask:0xc bank_mask:0xf
	v_add_f32_e32 v24, v24, v25
	s_nop 0
	v_readlane_b32 s36, v24, 63
	ds_read_b128 v[24:27], v28 offset:16
	s_waitcnt lgkmcnt(1)
	v_mul_f32_e32 v21, v9, v21
	v_fmac_f32_e32 v21, v8, v20
	v_mul_f32_e32 v20, v11, v23
	v_fmac_f32_e32 v20, v10, v22
	v_add_f32_e32 v20, v21, v20
	s_waitcnt lgkmcnt(0)
	v_mul_f32_e32 v25, v5, v25
	v_add_f32_e32 v29, 0, v20
	v_fmac_f32_e32 v25, v4, v24
	v_mul_f32_e32 v24, v7, v27
	ds_read_b128 v[20:23], v28 offset:2048
	v_fmac_f32_e32 v24, v6, v26
	v_add_f32_e32 v24, v25, v24
	v_add_f32_e32 v29, v29, v24
	ds_read_b128 v[24:27], v28 offset:2064
	s_waitcnt lgkmcnt(1)
	v_mul_f32_e32 v21, v13, v21
	v_fmac_f32_e32 v21, v12, v20
	v_mul_f32_e32 v20, v15, v23
	v_fmac_f32_e32 v20, v14, v22
	v_add_f32_e32 v20, v21, v20
	s_waitcnt lgkmcnt(0)
; #define LAS __attribute__((address_space(3)))
; __device__ __forceinline__ float wave_sum(float v) { return rdlane(dpp_sum63(v), 63); }
; __device__ __forceinline__ void row_finalize(CArgs& A, Frame& F, int m, const f32x4 (&v)[4], int Ln) {
;     ...
;     for (int c = 0; c < 8; ++c) { float s = 0.f;
; #pragma unroll
;         for (int j = 0; j < 4; ++j) { const f32x4 w = *(const LAS f32x4*)(wig + c * 1024 + RCOL(F.lane, j)); s += (v[j][0] * w[0] + v[j][1] * w[1]) + (v[j][2] * w[2] + v[j][3] * w[3]); }
;         r[c] = wave_sum(s); if (c & 1) asm volatile("" ::: "memory"); }
;     if (F.lane < 8) { float x = r[0];
; #pragma unroll
;         for (int c = 1; c < 8; ++c) x = (F.lane == c) ? r[c] : x;
;         WSP(float, WS_IGFG)[(size_t)m * 8 + F.lane] = x + b_in[F.lane]; }
	v_mul_f32_e32 v21, v17, v25
	v_mul_f32_e32 v22, v19, v27
	v_fmac_f32_e32 v21, v16, v24
	v_fmac_f32_e32 v22, v18, v26
	v_add_f32_e32 v20, v29, v20
	v_add_f32_e32 v21, v21, v22
	v_add_f32_e32 v20, v20, v21
	v_mov_b32_e32 v21, v2
	s_nop 0
	v_add_f32_dpp v20, v20, v20 quad_perm:[1,0,3,2] row_mask:0xf bank_mask:0xf bound_ctrl:1
	s_nop 1
	v_add_f32_dpp v20, v20, v20 quad_perm:[2,3,0,1] row_mask:0xf bank_mask:0xf bound_ctrl:1
	s_nop 1
	v_add_f32_dpp v20, v20, v20 row_half_mirror row_mask:0xf bank_mask:0xf bound_ctrl:1
	s_nop 1
	v_add_f32_dpp v20, v20, v20 row_mirror row_mask:0xf bank_mask:0xf bound_ctrl:1
	s_nop 1
	v_mov_b32_dpp v21, v20 row_bcast:15 row_mask:0xa bank_mask:0xf
	v_add_f32_e32 v20, v20, v21
	v_mov_b32_e32 v21, v2
	s_nop 1
	v_mov_b32_dpp v21, v20 row_bcast:31 row_mask:0xc bank_mask:0xf
	v_add_f32_e32 v24, v20, v21
	ds_read_b128 v[20:23], v32
	v_readlane_b32 s37, v24, 63
	ds_read_b128 v[24:27], v32 offset:2064
	ds_read_b128 v[28:31], v32 offset:2048
	ds_read_b128 v[32:35], v32 offset:16
	s_waitcnt lgkmcnt(3)
	v_mul_f32_e32 v21, v9, v21
	v_fmac_f32_e32 v21, v8, v20
	v_mul_f32_e32 v20, v11, v23
	v_fmac_f32_e32 v20, v10, v22
	v_add_f32_e32 v20, v21, v20
	s_waitcnt lgkmcnt(0)
	v_mul_f32_e32 v21, v5, v33
	v_mul_f32_e32 v22, v7, v35
	v_fmac_f32_e32 v21, v4, v32
	v_fmac_f32_e32 v22, v6, v34
	v_add_f32_e32 v20, 0, v20
	v_add_f32_e32 v21, v21, v22
	v_add_f32_e32 v20, v21, v20
	v_mul_f32_e32 v21, v13, v29
	v_mul_f32_e32 v22, v15, v31
	v_fmac_f32_e32 v21, v12, v28
	v_fmac_f32_e32 v22, v14, v30
	v_add_f32_e32 v21, v21, v22
	v_add_f32_e32 v20, v21, v20
	v_mul_f32_e32 v21, v17, v25
	v_mul_f32_e32 v22, v19, v27
	v_fmac_f32_e32 v21, v16, v24
	v_fmac_f32_e32 v22, v18, v26
	v_add_f32_e32 v21, v21, v22
	v_add_f32_e32 v20, v21, v20
	v_mov_b32_e32 v21, v2
	v_mov_b32_e32 v25, v2
	v_add_f32_dpp v20, v20, v20 quad_perm:[1,0,3,2] row_mask:0xf bank_mask:0xf bound_ctrl:1
	v_add_u32_e32 v28, 0x19000, v36
	s_nop 0
	v_add_f32_dpp v20, v20, v20 quad_perm:[2,3,0,1] row_mask:0xf bank_mask:0xf bound_ctrl:1
	s_nop 1
	v_add_f32_dpp v20, v20, v20 row_half_mirror row_mask:0xf bank_mask:0xf bound_ctrl:1
	s_nop 1
	v_add_f32_dpp v20, v20, v20 row_mirror row_mask:0xf bank_mask:0xf bound_ctrl:1
	s_nop 1
	v_mov_b32_dpp v21, v20 row_bcast:15 row_mask:0xa bank_mask:0xf
	v_add_f32_e32 v24, v20, v21
	ds_read_b128 v[20:23], v28
	s_nop 0
	v_mov_b32_dpp v25, v24 row_bcast:31 row_mask:0xc bank_mask:0xf
	v_add_f32_e32 v24, v24, v25
	s_nop 0
	v_readlane_b32 s54, v24, 63
	ds_read_b128 v[24:27], v28 offset:16
	s_waitcnt lgkmcnt(1)
	v_mul_f32_e32 v9, v9, v21
	v_fmac_f32_e32 v9, v8, v20
	v_mul_f32_e32 v8, v11, v23
	v_fmac_f32_e32 v8, v10, v22
	s_waitcnt lgkmcnt(0)
	v_mul_f32_e32 v5, v5, v25
	v_fmac_f32_e32 v5, v4, v24
	v_mul_f32_e32 v4, v7, v27
	v_add_f32_e32 v8, v9, v8
	v_fmac_f32_e32 v4, v6, v26
	v_add_f32_e32 v20, 0, v8
	ds_read_b128 v[8:11], v28 offset:2048
	v_add_f32_e32 v4, v5, v4
	v_add_f32_e32 v20, v20, v4
	ds_read_b128 v[4:7], v28 offset:2064
	s_waitcnt lgkmcnt(1)
	v_mul_f32_e32 v9, v13, v9
	v_fmac_f32_e32 v9, v12, v8
	v_mul_f32_e32 v8, v15, v11
	s_waitcnt lgkmcnt(0)
	v_mul_f32_e32 v5, v17, v5
	v_fmac_f32_e32 v8, v14, v10
	v_fmac_f32_e32 v5, v16, v4
	v_mul_f32_e32 v4, v19, v7
	v_add_f32_e32 v8, v9, v8
	v_fmac_f32_e32 v4, v18, v6
	v_add_f32_e32 v8, v20, v8
	v_add_f32_e32 v4, v5, v4
	v_add_f32_e32 v4, v8, v4
	v_mov_b32_e32 v5, v2
	s_nop 0
	v_add_f32_dpp v4, v4, v4 quad_perm:[1,0,3,2] row_mask:0xf bank_mask:0xf bound_ctrl:1
	s_nop 1
	v_add_f32_dpp v4, v4, v4 quad_perm:[2,3,0,1] row_mask:0xf bank_mask:0xf bound_ctrl:1
	s_nop 1
	v_add_f32_dpp v4, v4, v4 row_half_mirror row_mask:0xf bank_mask:0xf bound_ctrl:1
	s_nop 1
	v_add_f32_dpp v4, v4, v4 row_mirror row_mask:0xf bank_mask:0xf bound_ctrl:1
	s_nop 1
	v_mov_b32_dpp v5, v4 row_bcast:15 row_mask:0xa bank_mask:0xf
	v_add_f32_e32 v4, v4, v5
	v_mov_b32_e32 v5, v2
	s_nop 1
	v_mov_b32_dpp v5, v4 row_bcast:31 row_mask:0xc bank_mask:0xf
	v_add_f32_e32 v4, v4, v5
	s_nop 0
	v_readlane_b32 s55, v4, 63
	s_and_saveexec_b64 s[10:11], s[38:39]
	s_cbranch_execz .LBB0_1695
	s_load_dwordx2 s[56:57], s[2:3], 0x50
	v_mov_b32_e32 v4, s7
	v_mov_b32_e32 v5, s27
	v_cndmask_b32_e64 v4, v4, v5, s[40:41]
	v_mov_b32_e32 v5, s28
	v_cndmask_b32_e64 v4, v4, v5, s[42:43]
	v_mov_b32_e32 v5, s29
	v_cndmask_b32_e64 v4, v4, v5, s[44:45]
	v_mov_b32_e32 v5, s36
	v_cndmask_b32_e64 v4, v4, v5, s[46:47]
	v_mov_b32_e32 v5, s37
	s_waitcnt lgkmcnt(0)
	s_add_u32 s56, s56, s26
	v_cndmask_b32_e64 v4, v4, v5, s[48:49]
	v_mov_b32_e32 v5, s54
	s_addc_u32 s57, s57, s13
	v_cndmask_b32_e64 v4, v4, v5, s[50:51]
	v_mov_b32_e32 v5, s55
	v_cndmask_b32_e64 v6, v4, v5, s[52:53]
	v_lshl_add_u64 v[4:5], v[0:1], 2, s[56:57]
	v_add_co_u32_e32 v4, vcc, 0x3000, v4
	s_nop 1
	v_addc_co_u32_e32 v5, vcc, 0, v5, vcc
	v_mov_b32_e32 v4, v168
	s_nop 0
	v_add_f32_e32 v6, v6, v4
	v_lshl_add_u64 v[4:5], s[58:59], 0, v[64:65]
	global_store_dword v[4:5], v6, off
	s_branch .LBB0_1695
